# EpiResidual epilogues (P4, down0, P10, down1): base loads hoisted and software-pipelined 3 rows deep with counted vmcnt instead of 32 serialized vmcnt(0) round trips
# speedup vs baseline: 1.0231x; 1.0231x over previous
.LBB0_1696:
	v_lshl_add_u32 v142, s72, 8, v144
	v_lshl_add_u32 v140, s18, 8, v146
	v_lshl_add_u32 v210, v142, 11, v140
	v_lshlrev_b32_e32 v210, 2, v210
	global_load_dwordx4 v[162:165], v210, s[14:15]
	global_load_dwordx4 v[166:169], v210, s[14:15] offset:64
	global_load_dwordx4 v[170:173], v210, s[14:15] offset:512
	global_load_dwordx4 v[174:177], v210, s[14:15] offset:576
	v_add_u32_e32 v211, 0x20000, v210
	global_load_dwordx4 v[178:181], v211, s[14:15]
	global_load_dwordx4 v[182:185], v211, s[14:15] offset:64
	global_load_dwordx4 v[186:189], v211, s[14:15] offset:512
	global_load_dwordx4 v[190:193], v211, s[14:15] offset:576
	v_add_u32_e32 v211, 0x40000, v210
	global_load_dwordx4 v[194:197], v211, s[14:15]
	global_load_dwordx4 v[198:201], v211, s[14:15] offset:64
	global_load_dwordx4 v[202:205], v211, s[14:15] offset:512
	global_load_dwordx4 v[206:209], v211, s[14:15] offset:576
	v_ashrrev_i32_e32 v143, 31, v142
	v_ashrrev_i32_e32 v141, 31, v140
	v_lshlrev_b64 v[152:153], 11, v[142:143]
	v_lshl_add_u64 v[156:157], v[152:153], 0, v[140:141]
	v_lshlrev_b64 v[158:159], 2, v[156:157]
	v_lshl_add_u64 v[160:161], s[14:15], 0, v[158:159]
	s_nop 0
	v_lshl_add_u64 v[156:157], v[156:157], 1, s[54:55]
	v_lshl_add_u64 v[158:159], s[16:17], 0, v[158:159]
	s_lshl_b32 s72, s18, 2
	s_ashr_i32 s73, s72, 31
	s_waitcnt vmcnt(11)
	v_pk_add_f32 v[126:127], v[126:127], v[164:165]
	v_pk_add_f32 v[124:125], v[124:125], v[162:163]
	v_cvt_pk_bf16_f32 v153, v126, v127
	v_cvt_pk_bf16_f32 v152, v124, v125
	global_store_dwordx4 v[158:159], v[124:127], off
	global_store_dwordx2 v[156:157], v[152:153], off
	s_nop 0
	v_mul_f32_e32 v125, v125, v125
	v_mul_f32_e32 v127, v127, v127
	v_fmac_f32_e32 v125, v124, v124
	v_fmac_f32_e32 v127, v126, v126
	v_add_f32_e32 v124, v125, v127
	s_waitcnt vmcnt(12)
	v_pk_add_f32 v[122:123], v[122:123], v[168:169]
	v_pk_add_f32 v[120:121], v[120:121], v[166:167]
	v_cvt_pk_bf16_f32 v153, v122, v123
	v_cvt_pk_bf16_f32 v152, v120, v121
	global_store_dwordx4 v[158:159], v[120:123], off offset:64
	global_store_dwordx2 v[156:157], v[152:153], off offset:32
	s_nop 0
	v_mul_f32_e32 v121, v121, v121
	v_mul_f32_e32 v123, v123, v123
	v_fmac_f32_e32 v121, v120, v120
	v_fmac_f32_e32 v123, v122, v122
	v_add_f32_e32 v120, v121, v123
	v_add_f32_e32 v120, v124, v120
	s_waitcnt vmcnt(13)
	v_pk_add_f32 v[118:119], v[118:119], v[172:173]
	v_pk_add_f32 v[116:117], v[116:117], v[170:171]
	v_cvt_pk_bf16_f32 v153, v118, v119
	v_cvt_pk_bf16_f32 v152, v116, v117
	global_store_dwordx4 v[158:159], v[116:119], off offset:512
	global_store_dwordx2 v[156:157], v[152:153], off offset:256
	s_nop 0
	v_mul_f32_e32 v117, v117, v117
	v_mul_f32_e32 v119, v119, v119
	v_fmac_f32_e32 v117, v116, v116
	v_fmac_f32_e32 v119, v118, v118
	v_add_f32_e32 v116, v117, v119
	v_add_f32_e32 v118, v120, v116
	s_waitcnt vmcnt(14)
	v_pk_add_f32 v[116:117], v[114:115], v[176:177]
	v_pk_add_f32 v[114:115], v[112:113], v[174:175]
	v_add_u32_e32 v211, 0x60000, v210
	global_load_dwordx4 v[162:165], v211, s[14:15]
	global_load_dwordx4 v[166:169], v211, s[14:15] offset:64
	global_load_dwordx4 v[170:173], v211, s[14:15] offset:512
	global_load_dwordx4 v[174:177], v211, s[14:15] offset:576
	v_mul_f32_e32 v113, v117, v117
	v_mul_f32_e32 v112, v115, v115
	v_fmac_f32_e32 v112, v114, v114
	v_fmac_f32_e32 v113, v116, v116
	v_add_f32_e32 v112, v112, v113
	v_add_f32_e32 v112, v118, v112
	ds_bpermute_b32 v113, v147, v112
	global_store_dwordx4 v[158:159], v[114:117], off offset:576
	s_waitcnt lgkmcnt(0)
	v_add_f32_e32 v112, v112, v113
	ds_bpermute_b32 v113, v148, v112
	v_cvt_pk_bf16_f32 v114, v114, v115
	v_cvt_pk_bf16_f32 v115, v116, v117
	global_store_dwordx2 v[156:157], v[114:115], off offset:288
	s_and_saveexec_b64 s[74:75], s[10:11]
	s_cbranch_execz .LBB0_1698
	v_lshlrev_b64 v[114:115], 7, v[142:143]
	v_lshl_add_u64 v[114:115], s[52:53], 0, v[114:115]
	v_lshl_add_u64 v[114:115], s[72:73], 2, v[114:115]
	s_lshl_b32 s18, s3, 2
	v_lshl_add_u64 v[114:115], v[114:115], 0, s[18:19]
	s_waitcnt lgkmcnt(0)
	v_add_f32_e32 v112, v112, v113
	global_store_dword v[114:115], v112, off
.LBB0_1698:
	s_or_b64 exec, exec, s[74:75]
	v_or_b32_e32 v112, 16, v142
	s_waitcnt lgkmcnt(0)
	v_ashrrev_i32_e32 v113, 31, v112
	v_lshlrev_b64 v[114:115], 11, v[112:113]
	v_lshl_add_u64 v[118:119], v[114:115], 0, v[140:141]
	v_lshlrev_b64 v[120:121], 2, v[118:119]
	v_lshl_add_u64 v[122:123], s[14:15], 0, v[120:121]
	s_nop 0
	v_lshl_add_u64 v[118:119], v[118:119], 1, s[54:55]
	v_lshl_add_u64 v[120:121], s[16:17], 0, v[120:121]
	s_waitcnt vmcnt(19)
	v_pk_add_f32 v[110:111], v[110:111], v[180:181]
	v_pk_add_f32 v[108:109], v[108:109], v[178:179]
	v_cvt_pk_bf16_f32 v115, v110, v111
	v_cvt_pk_bf16_f32 v114, v108, v109
	global_store_dwordx4 v[120:121], v[108:111], off
	global_store_dwordx2 v[118:119], v[114:115], off
	s_nop 0
	v_mul_f32_e32 v109, v109, v109
	v_mul_f32_e32 v111, v111, v111
	v_fmac_f32_e32 v109, v108, v108
	v_fmac_f32_e32 v111, v110, v110
	v_add_f32_e32 v108, v109, v111
	s_waitcnt vmcnt(20)
	v_pk_add_f32 v[106:107], v[106:107], v[184:185]
	v_pk_add_f32 v[104:105], v[104:105], v[182:183]
	v_cvt_pk_bf16_f32 v115, v106, v107
	v_cvt_pk_bf16_f32 v114, v104, v105
	global_store_dwordx4 v[120:121], v[104:107], off offset:64
	global_store_dwordx2 v[118:119], v[114:115], off offset:32
	s_nop 0
	v_mul_f32_e32 v105, v105, v105
	v_mul_f32_e32 v107, v107, v107
	v_fmac_f32_e32 v105, v104, v104
	v_fmac_f32_e32 v107, v106, v106
	v_add_f32_e32 v104, v105, v107
	v_add_f32_e32 v104, v108, v104
	s_waitcnt vmcnt(21)
	v_pk_add_f32 v[102:103], v[102:103], v[188:189]
	v_pk_add_f32 v[100:101], v[100:101], v[186:187]
	v_cvt_pk_bf16_f32 v115, v102, v103
	v_cvt_pk_bf16_f32 v114, v100, v101
	global_store_dwordx4 v[120:121], v[100:103], off offset:512
	global_store_dwordx2 v[118:119], v[114:115], off offset:256
	s_nop 0
	v_mul_f32_e32 v101, v101, v101
	v_mul_f32_e32 v103, v103, v103
	v_fmac_f32_e32 v101, v100, v100
	v_fmac_f32_e32 v103, v102, v102
	v_add_f32_e32 v100, v101, v103
	v_add_f32_e32 v102, v104, v100
	s_waitcnt vmcnt(22)
	v_pk_add_f32 v[100:101], v[98:99], v[192:193]
	v_pk_add_f32 v[98:99], v[96:97], v[190:191]
	v_add_u32_e32 v211, 0x100000, v210
	global_load_dwordx4 v[178:181], v211, s[14:15]
	global_load_dwordx4 v[182:185], v211, s[14:15] offset:64
	global_load_dwordx4 v[186:189], v211, s[14:15] offset:512
	global_load_dwordx4 v[190:193], v211, s[14:15] offset:576
	v_mul_f32_e32 v97, v101, v101
	v_mul_f32_e32 v96, v99, v99
	v_fmac_f32_e32 v96, v98, v98
	v_fmac_f32_e32 v97, v100, v100
	v_add_f32_e32 v96, v96, v97
	v_add_f32_e32 v96, v102, v96
	ds_bpermute_b32 v97, v147, v96
	global_store_dwordx4 v[120:121], v[98:101], off offset:576
	s_waitcnt lgkmcnt(0)
	v_add_f32_e32 v96, v96, v97
	ds_bpermute_b32 v97, v148, v96
	v_cvt_pk_bf16_f32 v98, v98, v99
	v_cvt_pk_bf16_f32 v99, v100, v101
	global_store_dwordx2 v[118:119], v[98:99], off offset:288
	s_and_saveexec_b64 s[74:75], s[10:11]
	s_cbranch_execz .LBB0_1700
	v_lshlrev_b64 v[98:99], 7, v[112:113]
	v_lshl_add_u64 v[98:99], s[52:53], 0, v[98:99]
	v_lshl_add_u64 v[98:99], s[72:73], 2, v[98:99]
	s_lshl_b32 s18, s3, 2
	v_lshl_add_u64 v[98:99], v[98:99], 0, s[18:19]
	s_waitcnt lgkmcnt(0)
	v_add_f32_e32 v96, v96, v97
	global_store_dword v[98:99], v96, off
.LBB0_1700:
	s_or_b64 exec, exec, s[74:75]
	v_or_b32_e32 v96, 32, v142
	s_waitcnt lgkmcnt(0)
	v_ashrrev_i32_e32 v97, 31, v96
	v_lshlrev_b64 v[98:99], 11, v[96:97]
	v_lshl_add_u64 v[102:103], v[98:99], 0, v[140:141]
	v_lshlrev_b64 v[104:105], 2, v[102:103]
	v_lshl_add_u64 v[106:107], s[14:15], 0, v[104:105]
	s_nop 0
	v_lshl_add_u64 v[102:103], v[102:103], 1, s[54:55]
	v_lshl_add_u64 v[104:105], s[16:17], 0, v[104:105]
	s_waitcnt vmcnt(27)
	v_pk_add_f32 v[94:95], v[94:95], v[196:197]
	v_pk_add_f32 v[92:93], v[92:93], v[194:195]
	v_cvt_pk_bf16_f32 v99, v94, v95
	v_cvt_pk_bf16_f32 v98, v92, v93
	global_store_dwordx4 v[104:105], v[92:95], off
	global_store_dwordx2 v[102:103], v[98:99], off
	s_nop 0
	v_mul_f32_e32 v93, v93, v93
	v_mul_f32_e32 v95, v95, v95
	v_fmac_f32_e32 v93, v92, v92
	v_fmac_f32_e32 v95, v94, v94
	v_add_f32_e32 v92, v93, v95
	s_waitcnt vmcnt(28)
	v_pk_add_f32 v[90:91], v[90:91], v[200:201]
	v_pk_add_f32 v[88:89], v[88:89], v[198:199]
	v_cvt_pk_bf16_f32 v99, v90, v91
	v_cvt_pk_bf16_f32 v98, v88, v89
	global_store_dwordx4 v[104:105], v[88:91], off offset:64
	global_store_dwordx2 v[102:103], v[98:99], off offset:32
	s_nop 0
	v_mul_f32_e32 v89, v89, v89
	v_mul_f32_e32 v91, v91, v91
	v_fmac_f32_e32 v89, v88, v88
	v_fmac_f32_e32 v91, v90, v90
	v_add_f32_e32 v88, v89, v91
	v_add_f32_e32 v88, v92, v88
	s_waitcnt vmcnt(29)
	v_pk_add_f32 v[86:87], v[86:87], v[204:205]
	v_pk_add_f32 v[84:85], v[84:85], v[202:203]
	v_cvt_pk_bf16_f32 v99, v86, v87
	v_cvt_pk_bf16_f32 v98, v84, v85
	global_store_dwordx4 v[104:105], v[84:87], off offset:512
	global_store_dwordx2 v[102:103], v[98:99], off offset:256
	s_nop 0
	v_mul_f32_e32 v85, v85, v85
	v_mul_f32_e32 v87, v87, v87
	v_fmac_f32_e32 v85, v84, v84
	v_fmac_f32_e32 v87, v86, v86
	v_add_f32_e32 v84, v85, v87
	v_add_f32_e32 v86, v88, v84
	s_waitcnt vmcnt(30)
	v_pk_add_f32 v[84:85], v[82:83], v[208:209]
	v_pk_add_f32 v[82:83], v[80:81], v[206:207]
	v_add_u32_e32 v211, 0x120000, v210
	global_load_dwordx4 v[194:197], v211, s[14:15]
	global_load_dwordx4 v[198:201], v211, s[14:15] offset:64
	global_load_dwordx4 v[202:205], v211, s[14:15] offset:512
	global_load_dwordx4 v[206:209], v211, s[14:15] offset:576
	v_mul_f32_e32 v81, v85, v85
	v_mul_f32_e32 v80, v83, v83
	v_fmac_f32_e32 v80, v82, v82
	v_fmac_f32_e32 v81, v84, v84
	v_add_f32_e32 v80, v80, v81
	v_add_f32_e32 v80, v86, v80
	ds_bpermute_b32 v81, v147, v80
	global_store_dwordx4 v[104:105], v[82:85], off offset:576
	s_waitcnt lgkmcnt(0)
	v_add_f32_e32 v80, v80, v81
	ds_bpermute_b32 v81, v148, v80
	v_cvt_pk_bf16_f32 v82, v82, v83
	v_cvt_pk_bf16_f32 v83, v84, v85
	global_store_dwordx2 v[102:103], v[82:83], off offset:288
	s_and_saveexec_b64 s[74:75], s[10:11]
	s_cbranch_execz .LBB0_1702
	v_lshlrev_b64 v[82:83], 7, v[96:97]
	v_lshl_add_u64 v[82:83], s[52:53], 0, v[82:83]
	v_lshl_add_u64 v[82:83], s[72:73], 2, v[82:83]
	s_lshl_b32 s18, s3, 2
	v_lshl_add_u64 v[82:83], v[82:83], 0, s[18:19]
	s_waitcnt lgkmcnt(0)
	v_add_f32_e32 v80, v80, v81
	global_store_dword v[82:83], v80, off
.LBB0_1702:
	s_or_b64 exec, exec, s[74:75]
	v_or_b32_e32 v80, 48, v142
	s_waitcnt lgkmcnt(0)
	v_ashrrev_i32_e32 v81, 31, v80
	v_lshlrev_b64 v[82:83], 11, v[80:81]
	v_lshl_add_u64 v[86:87], v[82:83], 0, v[140:141]
	v_lshlrev_b64 v[88:89], 2, v[86:87]
	v_lshl_add_u64 v[90:91], s[14:15], 0, v[88:89]
	s_nop 0
	v_lshl_add_u64 v[86:87], v[86:87], 1, s[54:55]
	v_lshl_add_u64 v[88:89], s[16:17], 0, v[88:89]
	s_waitcnt vmcnt(29)
	v_pk_add_f32 v[78:79], v[78:79], v[164:165]
	v_pk_add_f32 v[76:77], v[76:77], v[162:163]
	v_cvt_pk_bf16_f32 v83, v78, v79
	v_cvt_pk_bf16_f32 v82, v76, v77
	global_store_dwordx4 v[88:89], v[76:79], off
	global_store_dwordx2 v[86:87], v[82:83], off
	s_nop 0
	v_mul_f32_e32 v77, v77, v77
	v_mul_f32_e32 v79, v79, v79
	v_fmac_f32_e32 v77, v76, v76
	v_fmac_f32_e32 v79, v78, v78
	v_add_f32_e32 v76, v77, v79
	s_waitcnt vmcnt(30)
	v_pk_add_f32 v[74:75], v[74:75], v[168:169]
	v_pk_add_f32 v[72:73], v[72:73], v[166:167]
	v_cvt_pk_bf16_f32 v83, v74, v75
	v_cvt_pk_bf16_f32 v82, v72, v73
	global_store_dwordx4 v[88:89], v[72:75], off offset:64
	global_store_dwordx2 v[86:87], v[82:83], off offset:32
	s_nop 0
	v_mul_f32_e32 v73, v73, v73
	v_mul_f32_e32 v75, v75, v75
	v_fmac_f32_e32 v73, v72, v72
	v_fmac_f32_e32 v75, v74, v74
	v_add_f32_e32 v72, v73, v75
	v_add_f32_e32 v72, v76, v72
	s_waitcnt vmcnt(31)
	v_pk_add_f32 v[70:71], v[70:71], v[172:173]
	v_pk_add_f32 v[68:69], v[68:69], v[170:171]
	v_cvt_pk_bf16_f32 v83, v70, v71
	v_cvt_pk_bf16_f32 v82, v68, v69
	global_store_dwordx4 v[88:89], v[68:71], off offset:512
	global_store_dwordx2 v[86:87], v[82:83], off offset:256
	s_nop 0
	v_mul_f32_e32 v69, v69, v69
	v_mul_f32_e32 v71, v71, v71
	v_fmac_f32_e32 v69, v68, v68
	v_fmac_f32_e32 v71, v70, v70
	v_add_f32_e32 v68, v69, v71
	v_add_f32_e32 v70, v72, v68
	s_waitcnt vmcnt(32)
	v_pk_add_f32 v[68:69], v[66:67], v[176:177]
	v_pk_add_f32 v[66:67], v[64:65], v[174:175]
	v_add_u32_e32 v211, 0x140000, v210
	global_load_dwordx4 v[162:165], v211, s[14:15]
	global_load_dwordx4 v[166:169], v211, s[14:15] offset:64
	global_load_dwordx4 v[170:173], v211, s[14:15] offset:512
	global_load_dwordx4 v[174:177], v211, s[14:15] offset:576
	v_mul_f32_e32 v65, v69, v69
	v_mul_f32_e32 v64, v67, v67
	v_fmac_f32_e32 v64, v66, v66
	v_fmac_f32_e32 v65, v68, v68
	v_add_f32_e32 v64, v64, v65
	v_add_f32_e32 v64, v70, v64
	ds_bpermute_b32 v65, v147, v64
	global_store_dwordx4 v[88:89], v[66:69], off offset:576
	s_waitcnt lgkmcnt(0)
	v_add_f32_e32 v64, v64, v65
	ds_bpermute_b32 v65, v148, v64
	v_cvt_pk_bf16_f32 v66, v66, v67
	v_cvt_pk_bf16_f32 v67, v68, v69
	global_store_dwordx2 v[86:87], v[66:67], off offset:288
	s_and_saveexec_b64 s[74:75], s[10:11]
	s_cbranch_execz .LBB0_1704
	v_lshlrev_b64 v[66:67], 7, v[80:81]
	v_lshl_add_u64 v[66:67], s[52:53], 0, v[66:67]
	v_lshl_add_u64 v[66:67], s[72:73], 2, v[66:67]
	s_lshl_b32 s18, s3, 2
	v_lshl_add_u64 v[66:67], v[66:67], 0, s[18:19]
	s_waitcnt lgkmcnt(0)
	v_add_f32_e32 v64, v64, v65
	global_store_dword v[66:67], v64, off
.LBB0_1704:
	s_or_b64 exec, exec, s[74:75]
	v_add_u32_e32 v64, 0x80, v142
	s_waitcnt lgkmcnt(0)
	v_ashrrev_i32_e32 v65, 31, v64
	v_lshlrev_b64 v[66:67], 11, v[64:65]
	v_lshl_add_u64 v[70:71], v[66:67], 0, v[140:141]
	v_lshlrev_b64 v[72:73], 2, v[70:71]
	v_lshl_add_u64 v[74:75], s[14:15], 0, v[72:73]
	s_nop 0
	v_lshl_add_u64 v[70:71], v[70:71], 1, s[54:55]
	v_lshl_add_u64 v[72:73], s[16:17], 0, v[72:73]
	s_waitcnt vmcnt(29)
	v_pk_add_f32 v[62:63], v[62:63], v[180:181]
	v_pk_add_f32 v[60:61], v[60:61], v[178:179]
	v_cvt_pk_bf16_f32 v67, v62, v63
	v_cvt_pk_bf16_f32 v66, v60, v61
	global_store_dwordx4 v[72:73], v[60:63], off
	global_store_dwordx2 v[70:71], v[66:67], off
	s_nop 0
	v_mul_f32_e32 v61, v61, v61
	v_mul_f32_e32 v63, v63, v63
	v_fmac_f32_e32 v61, v60, v60
	v_fmac_f32_e32 v63, v62, v62
	v_add_f32_e32 v60, v61, v63
	s_waitcnt vmcnt(30)
	v_pk_add_f32 v[58:59], v[58:59], v[184:185]
	v_pk_add_f32 v[56:57], v[56:57], v[182:183]
	v_cvt_pk_bf16_f32 v67, v58, v59
	v_cvt_pk_bf16_f32 v66, v56, v57
	global_store_dwordx4 v[72:73], v[56:59], off offset:64
	global_store_dwordx2 v[70:71], v[66:67], off offset:32
	s_nop 0
	v_mul_f32_e32 v57, v57, v57
	v_mul_f32_e32 v59, v59, v59
	v_fmac_f32_e32 v57, v56, v56
	v_fmac_f32_e32 v59, v58, v58
	v_add_f32_e32 v56, v57, v59
	v_add_f32_e32 v56, v60, v56
	s_waitcnt vmcnt(31)
	v_pk_add_f32 v[54:55], v[54:55], v[188:189]
	v_pk_add_f32 v[52:53], v[52:53], v[186:187]
	v_cvt_pk_bf16_f32 v67, v54, v55
	v_cvt_pk_bf16_f32 v66, v52, v53
	global_store_dwordx4 v[72:73], v[52:55], off offset:512
	global_store_dwordx2 v[70:71], v[66:67], off offset:256
	s_nop 0
	v_mul_f32_e32 v53, v53, v53
	v_mul_f32_e32 v55, v55, v55
	v_fmac_f32_e32 v53, v52, v52
	v_fmac_f32_e32 v55, v54, v54
	v_add_f32_e32 v52, v53, v55
	v_add_f32_e32 v54, v56, v52
	s_waitcnt vmcnt(32)
	v_pk_add_f32 v[52:53], v[50:51], v[192:193]
	v_pk_add_f32 v[50:51], v[48:49], v[190:191]
	v_add_u32_e32 v211, 0x160000, v210
	global_load_dwordx4 v[178:181], v211, s[14:15]
	global_load_dwordx4 v[182:185], v211, s[14:15] offset:64
	global_load_dwordx4 v[186:189], v211, s[14:15] offset:512
	global_load_dwordx4 v[190:193], v211, s[14:15] offset:576
	v_mul_f32_e32 v49, v53, v53
	v_mul_f32_e32 v48, v51, v51
	v_fmac_f32_e32 v48, v50, v50
	v_fmac_f32_e32 v49, v52, v52
	v_add_f32_e32 v48, v48, v49
	v_add_f32_e32 v48, v54, v48
	ds_bpermute_b32 v49, v147, v48
	global_store_dwordx4 v[72:73], v[50:53], off offset:576
	s_waitcnt lgkmcnt(0)
	v_add_f32_e32 v48, v48, v49
	ds_bpermute_b32 v49, v148, v48
	v_cvt_pk_bf16_f32 v50, v50, v51
	v_cvt_pk_bf16_f32 v51, v52, v53
	global_store_dwordx2 v[70:71], v[50:51], off offset:288
	s_and_saveexec_b64 s[74:75], s[10:11]
	s_cbranch_execz .LBB0_1706
	v_lshlrev_b64 v[50:51], 7, v[64:65]
	v_lshl_add_u64 v[50:51], s[52:53], 0, v[50:51]
	v_lshl_add_u64 v[50:51], s[72:73], 2, v[50:51]
	s_lshl_b32 s18, s3, 2
	v_lshl_add_u64 v[50:51], v[50:51], 0, s[18:19]
	s_waitcnt lgkmcnt(0)
	v_add_f32_e32 v48, v48, v49
	global_store_dword v[50:51], v48, off
.LBB0_1706:
	s_or_b64 exec, exec, s[74:75]
	v_add_u32_e32 v48, 0x90, v142
	s_waitcnt lgkmcnt(0)
	v_ashrrev_i32_e32 v49, 31, v48
	v_lshlrev_b64 v[50:51], 11, v[48:49]
	v_lshl_add_u64 v[54:55], v[50:51], 0, v[140:141]
	v_lshlrev_b64 v[56:57], 2, v[54:55]
	v_lshl_add_u64 v[58:59], s[14:15], 0, v[56:57]
	s_nop 0
	v_lshl_add_u64 v[54:55], v[54:55], 1, s[54:55]
	v_lshl_add_u64 v[56:57], s[16:17], 0, v[56:57]
	s_waitcnt vmcnt(29)
	v_pk_add_f32 v[46:47], v[46:47], v[196:197]
	v_pk_add_f32 v[44:45], v[44:45], v[194:195]
	v_cvt_pk_bf16_f32 v51, v46, v47
	v_cvt_pk_bf16_f32 v50, v44, v45
	global_store_dwordx4 v[56:57], v[44:47], off
	global_store_dwordx2 v[54:55], v[50:51], off
	s_nop 0
	v_mul_f32_e32 v45, v45, v45
	v_mul_f32_e32 v47, v47, v47
	v_fmac_f32_e32 v45, v44, v44
	v_fmac_f32_e32 v47, v46, v46
	v_add_f32_e32 v44, v45, v47
	s_waitcnt vmcnt(30)
	v_pk_add_f32 v[42:43], v[42:43], v[200:201]
	v_pk_add_f32 v[40:41], v[40:41], v[198:199]
	v_cvt_pk_bf16_f32 v51, v42, v43
	v_cvt_pk_bf16_f32 v50, v40, v41
	global_store_dwordx4 v[56:57], v[40:43], off offset:64
	global_store_dwordx2 v[54:55], v[50:51], off offset:32
	s_nop 0
	v_mul_f32_e32 v41, v41, v41
	v_mul_f32_e32 v43, v43, v43
	v_fmac_f32_e32 v41, v40, v40
	v_fmac_f32_e32 v43, v42, v42
	v_add_f32_e32 v40, v41, v43
	v_add_f32_e32 v40, v44, v40
	s_waitcnt vmcnt(31)
	v_pk_add_f32 v[38:39], v[38:39], v[204:205]
	v_pk_add_f32 v[36:37], v[36:37], v[202:203]
	v_cvt_pk_bf16_f32 v51, v38, v39
	v_cvt_pk_bf16_f32 v50, v36, v37
	global_store_dwordx4 v[56:57], v[36:39], off offset:512
	global_store_dwordx2 v[54:55], v[50:51], off offset:256
	s_nop 0
	v_mul_f32_e32 v37, v37, v37
	v_mul_f32_e32 v39, v39, v39
	v_fmac_f32_e32 v37, v36, v36
	v_fmac_f32_e32 v39, v38, v38
	v_add_f32_e32 v36, v37, v39
	v_add_f32_e32 v38, v40, v36
	s_waitcnt vmcnt(32)
	v_pk_add_f32 v[36:37], v[34:35], v[208:209]
	v_pk_add_f32 v[34:35], v[32:33], v[206:207]
	v_mul_f32_e32 v33, v37, v37
	v_mul_f32_e32 v32, v35, v35
	v_fmac_f32_e32 v32, v34, v34
	v_fmac_f32_e32 v33, v36, v36
	v_add_f32_e32 v32, v32, v33
	v_add_f32_e32 v32, v38, v32
	ds_bpermute_b32 v33, v147, v32
	global_store_dwordx4 v[56:57], v[34:37], off offset:576
	s_waitcnt lgkmcnt(0)
	v_add_f32_e32 v32, v32, v33
	ds_bpermute_b32 v33, v148, v32
	v_cvt_pk_bf16_f32 v34, v34, v35
	v_cvt_pk_bf16_f32 v35, v36, v37
	global_store_dwordx2 v[54:55], v[34:35], off offset:288
	s_and_saveexec_b64 s[74:75], s[10:11]
	s_cbranch_execz .LBB0_1708
	v_lshlrev_b64 v[34:35], 7, v[48:49]
	v_lshl_add_u64 v[34:35], s[52:53], 0, v[34:35]
	v_lshl_add_u64 v[34:35], s[72:73], 2, v[34:35]
	s_lshl_b32 s18, s3, 2
	v_lshl_add_u64 v[34:35], v[34:35], 0, s[18:19]
	s_waitcnt lgkmcnt(0)
	v_add_f32_e32 v32, v32, v33
	global_store_dword v[34:35], v32, off
.LBB0_1708:
	s_or_b64 exec, exec, s[74:75]
	v_add_u32_e32 v32, 0xa0, v142
	s_waitcnt lgkmcnt(0)
	v_ashrrev_i32_e32 v33, 31, v32
	v_lshlrev_b64 v[34:35], 11, v[32:33]
	v_lshl_add_u64 v[38:39], v[34:35], 0, v[140:141]
	v_lshlrev_b64 v[40:41], 2, v[38:39]
	v_lshl_add_u64 v[42:43], s[14:15], 0, v[40:41]
	s_nop 0
	v_lshl_add_u64 v[38:39], v[38:39], 1, s[54:55]
	v_lshl_add_u64 v[40:41], s[16:17], 0, v[40:41]
	s_waitcnt vmcnt(25)
	v_pk_add_f32 v[30:31], v[30:31], v[164:165]
	v_pk_add_f32 v[28:29], v[28:29], v[162:163]
	v_cvt_pk_bf16_f32 v35, v30, v31
	v_cvt_pk_bf16_f32 v34, v28, v29
	global_store_dwordx4 v[40:41], v[28:31], off
	global_store_dwordx2 v[38:39], v[34:35], off
	s_nop 0
	v_mul_f32_e32 v29, v29, v29
	v_mul_f32_e32 v31, v31, v31
	v_fmac_f32_e32 v29, v28, v28
	v_fmac_f32_e32 v31, v30, v30
	v_add_f32_e32 v28, v29, v31
	s_waitcnt vmcnt(26)
	v_pk_add_f32 v[26:27], v[26:27], v[168:169]
	v_pk_add_f32 v[24:25], v[24:25], v[166:167]
	v_cvt_pk_bf16_f32 v35, v26, v27
	v_cvt_pk_bf16_f32 v34, v24, v25
	global_store_dwordx4 v[40:41], v[24:27], off offset:64
	global_store_dwordx2 v[38:39], v[34:35], off offset:32
	s_nop 0
	v_mul_f32_e32 v25, v25, v25
	v_mul_f32_e32 v27, v27, v27
	v_fmac_f32_e32 v25, v24, v24
	v_fmac_f32_e32 v27, v26, v26
	v_add_f32_e32 v24, v25, v27
	v_add_f32_e32 v24, v28, v24
	s_waitcnt vmcnt(27)
	v_pk_add_f32 v[22:23], v[22:23], v[172:173]
	v_pk_add_f32 v[20:21], v[20:21], v[170:171]
	v_cvt_pk_bf16_f32 v35, v22, v23
	v_cvt_pk_bf16_f32 v34, v20, v21
	global_store_dwordx4 v[40:41], v[20:23], off offset:512
	global_store_dwordx2 v[38:39], v[34:35], off offset:256
	s_nop 0
	v_mul_f32_e32 v21, v21, v21
	v_mul_f32_e32 v23, v23, v23
	v_fmac_f32_e32 v21, v20, v20
	v_fmac_f32_e32 v23, v22, v22
	v_add_f32_e32 v20, v21, v23
	v_add_f32_e32 v22, v24, v20
	s_waitcnt vmcnt(28)
	v_pk_add_f32 v[20:21], v[18:19], v[176:177]
	v_pk_add_f32 v[18:19], v[16:17], v[174:175]
	v_mul_f32_e32 v17, v21, v21
	v_mul_f32_e32 v16, v19, v19
	v_fmac_f32_e32 v16, v18, v18
	v_fmac_f32_e32 v17, v20, v20
	v_add_f32_e32 v16, v16, v17
	v_add_f32_e32 v16, v22, v16
	ds_bpermute_b32 v17, v147, v16
	global_store_dwordx4 v[40:41], v[18:21], off offset:576
	s_waitcnt lgkmcnt(0)
	v_add_f32_e32 v16, v16, v17
	ds_bpermute_b32 v17, v148, v16
	v_cvt_pk_bf16_f32 v18, v18, v19
	v_cvt_pk_bf16_f32 v19, v20, v21
	global_store_dwordx2 v[38:39], v[18:19], off offset:288
	s_and_saveexec_b64 s[74:75], s[10:11]
	s_cbranch_execz .LBB0_1710
	v_lshlrev_b64 v[18:19], 7, v[32:33]
	v_lshl_add_u64 v[18:19], s[52:53], 0, v[18:19]
	v_lshl_add_u64 v[18:19], s[72:73], 2, v[18:19]
	s_lshl_b32 s18, s3, 2
	v_lshl_add_u64 v[18:19], v[18:19], 0, s[18:19]
	s_waitcnt lgkmcnt(0)
	v_add_f32_e32 v16, v16, v17
	global_store_dword v[18:19], v16, off
.LBB0_1710:
	s_or_b64 exec, exec, s[74:75]
	v_add_u32_e32 v16, 0xb0, v142
	s_waitcnt lgkmcnt(0)
	v_ashrrev_i32_e32 v17, 31, v16
	v_lshlrev_b64 v[18:19], 11, v[16:17]
	v_lshl_add_u64 v[22:23], v[18:19], 0, v[140:141]
	v_lshlrev_b64 v[24:25], 2, v[22:23]
	v_lshl_add_u64 v[26:27], s[14:15], 0, v[24:25]
	s_nop 0
	v_lshl_add_u64 v[22:23], v[22:23], 1, s[54:55]
	v_lshl_add_u64 v[24:25], s[16:17], 0, v[24:25]
	s_waitcnt vmcnt(21)
	v_pk_add_f32 v[14:15], v[14:15], v[180:181]
	v_pk_add_f32 v[12:13], v[12:13], v[178:179]
	v_cvt_pk_bf16_f32 v19, v14, v15
	v_cvt_pk_bf16_f32 v18, v12, v13
	global_store_dwordx4 v[24:25], v[12:15], off
	global_store_dwordx2 v[22:23], v[18:19], off
	s_nop 0
	v_mul_f32_e32 v13, v13, v13
	v_mul_f32_e32 v15, v15, v15
	v_fmac_f32_e32 v13, v12, v12
	v_fmac_f32_e32 v15, v14, v14
	v_add_f32_e32 v12, v13, v15
	s_waitcnt vmcnt(22)
	v_pk_add_f32 v[10:11], v[10:11], v[184:185]
	v_pk_add_f32 v[8:9], v[8:9], v[182:183]
	v_cvt_pk_bf16_f32 v19, v10, v11
	v_cvt_pk_bf16_f32 v18, v8, v9
	global_store_dwordx4 v[24:25], v[8:11], off offset:64
	global_store_dwordx2 v[22:23], v[18:19], off offset:32
	s_nop 0
	v_mul_f32_e32 v9, v9, v9
	v_mul_f32_e32 v11, v11, v11
	v_fmac_f32_e32 v9, v8, v8
	v_fmac_f32_e32 v11, v10, v10
	v_add_f32_e32 v8, v9, v11
	v_add_f32_e32 v8, v12, v8
	s_waitcnt vmcnt(23)
	v_pk_add_f32 v[6:7], v[6:7], v[188:189]
	v_pk_add_f32 v[4:5], v[4:5], v[186:187]
	v_cvt_pk_bf16_f32 v19, v6, v7
	v_cvt_pk_bf16_f32 v18, v4, v5
	global_store_dwordx4 v[24:25], v[4:7], off offset:512
	global_store_dwordx2 v[22:23], v[18:19], off offset:256
	s_nop 0
	v_mul_f32_e32 v5, v5, v5
	v_mul_f32_e32 v7, v7, v7
	v_fmac_f32_e32 v5, v4, v4
	v_fmac_f32_e32 v7, v6, v6
	v_add_f32_e32 v4, v5, v7
	v_add_f32_e32 v6, v8, v4
	s_waitcnt vmcnt(24)
	v_pk_add_f32 v[4:5], v[2:3], v[192:193]
	v_pk_add_f32 v[2:3], v[0:1], v[190:191]
	v_mul_f32_e32 v1, v5, v5
	v_mul_f32_e32 v0, v3, v3
	v_fmac_f32_e32 v0, v2, v2
	v_fmac_f32_e32 v1, v4, v4
	v_add_f32_e32 v0, v0, v1
	v_add_f32_e32 v0, v6, v0
	ds_bpermute_b32 v1, v147, v0
	global_store_dwordx4 v[24:25], v[2:5], off offset:576
	s_waitcnt lgkmcnt(0)
	v_add_f32_e32 v0, v0, v1
	ds_bpermute_b32 v1, v148, v0
	v_cvt_pk_bf16_f32 v2, v2, v3
	v_cvt_pk_bf16_f32 v3, v4, v5
	global_store_dwordx2 v[22:23], v[2:3], off offset:288
	s_and_saveexec_b64 s[74:75], s[10:11]
	s_cbranch_execz .LBB0_1712
	v_lshlrev_b64 v[2:3], 7, v[16:17]
	v_lshl_add_u64 v[2:3], s[52:53], 0, v[2:3]
	v_lshl_add_u64 v[2:3], s[72:73], 2, v[2:3]
	s_lshl_b32 s18, s3, 2
	v_lshl_add_u64 v[2:3], v[2:3], 0, s[18:19]
	s_waitcnt lgkmcnt(0)
	v_add_f32_e32 v0, v0, v1
	global_store_dword v[2:3], v0, off

.LBB0_1900:
	v_lshl_add_u32 v142, s70, 8, v144
	v_lshl_add_u32 v140, s20, 8, v146
	v_lshl_add_u32 v208, v142, 11, v140
	v_lshlrev_b32_e32 v208, 2, v208
	global_load_dwordx4 v[160:163], v208, s[18:19]
	global_load_dwordx4 v[164:167], v208, s[18:19] offset:64
	global_load_dwordx4 v[168:171], v208, s[18:19] offset:512
	global_load_dwordx4 v[172:175], v208, s[18:19] offset:576
	v_add_u32_e32 v209, 0x20000, v208
	global_load_dwordx4 v[176:179], v209, s[18:19]
	global_load_dwordx4 v[180:183], v209, s[18:19] offset:64
	global_load_dwordx4 v[184:187], v209, s[18:19] offset:512
	global_load_dwordx4 v[188:191], v209, s[18:19] offset:576
	v_add_u32_e32 v209, 0x40000, v208
	global_load_dwordx4 v[192:195], v209, s[18:19]
	global_load_dwordx4 v[196:199], v209, s[18:19] offset:64
	global_load_dwordx4 v[200:203], v209, s[18:19] offset:512
	global_load_dwordx4 v[204:207], v209, s[18:19] offset:576
	v_ashrrev_i32_e32 v143, 31, v142
	v_ashrrev_i32_e32 v141, 31, v140
	v_lshlrev_b64 v[152:153], 11, v[142:143]
	v_lshl_add_u64 v[156:157], v[152:153], 0, v[140:141]
	v_lshl_add_u64 v[158:159], v[156:157], 2, s[18:19]
	s_nop 0
	v_lshl_add_u64 v[156:157], v[156:157], 1, s[54:55]
	s_lshl_b32 s70, s20, 2
	s_ashr_i32 s71, s70, 31
	s_waitcnt vmcnt(11)
	v_pk_add_f32 v[126:127], v[126:127], v[162:163]
	v_pk_add_f32 v[124:125], v[124:125], v[160:161]
	v_cvt_pk_bf16_f32 v153, v126, v127
	v_cvt_pk_bf16_f32 v152, v124, v125
	global_store_dwordx4 v[158:159], v[124:127], off
	global_store_dwordx2 v[156:157], v[152:153], off
	s_nop 0
	v_mul_f32_e32 v125, v125, v125
	v_mul_f32_e32 v127, v127, v127
	v_fmac_f32_e32 v125, v124, v124
	v_fmac_f32_e32 v127, v126, v126
	v_add_f32_e32 v124, v125, v127
	s_waitcnt vmcnt(12)
	v_pk_add_f32 v[122:123], v[122:123], v[166:167]
	v_pk_add_f32 v[120:121], v[120:121], v[164:165]
	v_cvt_pk_bf16_f32 v153, v122, v123
	v_cvt_pk_bf16_f32 v152, v120, v121
	global_store_dwordx4 v[158:159], v[120:123], off offset:64
	global_store_dwordx2 v[156:157], v[152:153], off offset:32
	s_nop 0
	v_mul_f32_e32 v121, v121, v121
	v_mul_f32_e32 v123, v123, v123
	v_fmac_f32_e32 v121, v120, v120
	v_fmac_f32_e32 v123, v122, v122
	v_add_f32_e32 v120, v121, v123
	v_add_f32_e32 v120, v124, v120
	s_waitcnt vmcnt(13)
	v_pk_add_f32 v[118:119], v[118:119], v[170:171]
	v_pk_add_f32 v[116:117], v[116:117], v[168:169]
	v_cvt_pk_bf16_f32 v153, v118, v119
	v_cvt_pk_bf16_f32 v152, v116, v117
	global_store_dwordx4 v[158:159], v[116:119], off offset:512
	global_store_dwordx2 v[156:157], v[152:153], off offset:256
	s_nop 0
	v_mul_f32_e32 v117, v117, v117
	v_mul_f32_e32 v119, v119, v119
	v_fmac_f32_e32 v117, v116, v116
	v_fmac_f32_e32 v119, v118, v118
	v_add_f32_e32 v116, v117, v119
	v_add_f32_e32 v118, v120, v116
	s_waitcnt vmcnt(14)
	v_pk_add_f32 v[116:117], v[114:115], v[174:175]
	v_pk_add_f32 v[114:115], v[112:113], v[172:173]
	v_add_u32_e32 v209, 0x60000, v208
	global_load_dwordx4 v[160:163], v209, s[18:19]
	global_load_dwordx4 v[164:167], v209, s[18:19] offset:64
	global_load_dwordx4 v[168:171], v209, s[18:19] offset:512
	global_load_dwordx4 v[172:175], v209, s[18:19] offset:576
	v_mul_f32_e32 v113, v117, v117
	v_mul_f32_e32 v112, v115, v115
	v_fmac_f32_e32 v112, v114, v114
	v_fmac_f32_e32 v113, v116, v116
	v_add_f32_e32 v112, v112, v113
	v_add_f32_e32 v112, v118, v112
	ds_bpermute_b32 v113, v147, v112
	global_store_dwordx4 v[158:159], v[114:117], off offset:576
	s_waitcnt lgkmcnt(0)
	v_add_f32_e32 v112, v112, v113
	ds_bpermute_b32 v113, v148, v112
	v_cvt_pk_bf16_f32 v114, v114, v115
	v_cvt_pk_bf16_f32 v115, v116, v117
	global_store_dwordx2 v[156:157], v[114:115], off offset:288
	s_and_saveexec_b64 s[72:73], s[14:15]
	s_cbranch_execz .LBB0_1902
	v_lshlrev_b64 v[114:115], 7, v[142:143]
	v_lshl_add_u64 v[114:115], s[52:53], 0, v[114:115]
	v_lshl_add_u64 v[114:115], s[70:71], 2, v[114:115]
	s_lshl_b32 s20, s3, 2
	v_lshl_add_u64 v[114:115], v[114:115], 0, s[20:21]
	s_waitcnt lgkmcnt(0)
	v_add_f32_e32 v112, v112, v113
	global_store_dword v[114:115], v112, off
.LBB0_1902:
	s_or_b64 exec, exec, s[72:73]
	v_or_b32_e32 v112, 16, v142
	s_waitcnt lgkmcnt(0)
	v_ashrrev_i32_e32 v113, 31, v112
	v_lshlrev_b64 v[114:115], 11, v[112:113]
	v_lshl_add_u64 v[118:119], v[114:115], 0, v[140:141]
	v_lshl_add_u64 v[120:121], v[118:119], 2, s[18:19]
	s_nop 0
	v_lshl_add_u64 v[118:119], v[118:119], 1, s[54:55]
	s_waitcnt vmcnt(19)
	v_pk_add_f32 v[110:111], v[110:111], v[178:179]
	v_pk_add_f32 v[108:109], v[108:109], v[176:177]
	v_cvt_pk_bf16_f32 v115, v110, v111
	v_cvt_pk_bf16_f32 v114, v108, v109
	global_store_dwordx4 v[120:121], v[108:111], off
	global_store_dwordx2 v[118:119], v[114:115], off
	s_nop 0
	v_mul_f32_e32 v109, v109, v109
	v_mul_f32_e32 v111, v111, v111
	v_fmac_f32_e32 v109, v108, v108
	v_fmac_f32_e32 v111, v110, v110
	v_add_f32_e32 v108, v109, v111
	s_waitcnt vmcnt(20)
	v_pk_add_f32 v[106:107], v[106:107], v[182:183]
	v_pk_add_f32 v[104:105], v[104:105], v[180:181]
	v_cvt_pk_bf16_f32 v115, v106, v107
	v_cvt_pk_bf16_f32 v114, v104, v105
	global_store_dwordx4 v[120:121], v[104:107], off offset:64
	global_store_dwordx2 v[118:119], v[114:115], off offset:32
	s_nop 0
	v_mul_f32_e32 v105, v105, v105
	v_mul_f32_e32 v107, v107, v107
	v_fmac_f32_e32 v105, v104, v104
	v_fmac_f32_e32 v107, v106, v106
	v_add_f32_e32 v104, v105, v107
	v_add_f32_e32 v104, v108, v104
	s_waitcnt vmcnt(21)
	v_pk_add_f32 v[102:103], v[102:103], v[186:187]
	v_pk_add_f32 v[100:101], v[100:101], v[184:185]
	v_cvt_pk_bf16_f32 v115, v102, v103
	v_cvt_pk_bf16_f32 v114, v100, v101
	global_store_dwordx4 v[120:121], v[100:103], off offset:512
	global_store_dwordx2 v[118:119], v[114:115], off offset:256
	s_nop 0
	v_mul_f32_e32 v101, v101, v101
	v_mul_f32_e32 v103, v103, v103
	v_fmac_f32_e32 v101, v100, v100
	v_fmac_f32_e32 v103, v102, v102
	v_add_f32_e32 v100, v101, v103
	v_add_f32_e32 v102, v104, v100
	s_waitcnt vmcnt(22)
	v_pk_add_f32 v[100:101], v[98:99], v[190:191]
	v_pk_add_f32 v[98:99], v[96:97], v[188:189]
	v_add_u32_e32 v209, 0x100000, v208
	global_load_dwordx4 v[176:179], v209, s[18:19]
	global_load_dwordx4 v[180:183], v209, s[18:19] offset:64
	global_load_dwordx4 v[184:187], v209, s[18:19] offset:512
	global_load_dwordx4 v[188:191], v209, s[18:19] offset:576
	v_mul_f32_e32 v97, v101, v101
	v_mul_f32_e32 v96, v99, v99
	v_fmac_f32_e32 v96, v98, v98
	v_fmac_f32_e32 v97, v100, v100
	v_add_f32_e32 v96, v96, v97
	v_add_f32_e32 v96, v102, v96
	ds_bpermute_b32 v97, v147, v96
	global_store_dwordx4 v[120:121], v[98:101], off offset:576
	s_waitcnt lgkmcnt(0)
	v_add_f32_e32 v96, v96, v97
	ds_bpermute_b32 v97, v148, v96
	v_cvt_pk_bf16_f32 v98, v98, v99
	v_cvt_pk_bf16_f32 v99, v100, v101
	global_store_dwordx2 v[118:119], v[98:99], off offset:288
	s_and_saveexec_b64 s[72:73], s[14:15]
	s_cbranch_execz .LBB0_1904
	v_lshlrev_b64 v[98:99], 7, v[112:113]
	v_lshl_add_u64 v[98:99], s[52:53], 0, v[98:99]
	v_lshl_add_u64 v[98:99], s[70:71], 2, v[98:99]
	s_lshl_b32 s20, s3, 2
	v_lshl_add_u64 v[98:99], v[98:99], 0, s[20:21]
	s_waitcnt lgkmcnt(0)
	v_add_f32_e32 v96, v96, v97
	global_store_dword v[98:99], v96, off
.LBB0_1904:
	s_or_b64 exec, exec, s[72:73]
	v_or_b32_e32 v96, 32, v142
	s_waitcnt lgkmcnt(0)
	v_ashrrev_i32_e32 v97, 31, v96
	v_lshlrev_b64 v[98:99], 11, v[96:97]
	v_lshl_add_u64 v[102:103], v[98:99], 0, v[140:141]
	v_lshl_add_u64 v[104:105], v[102:103], 2, s[18:19]
	s_nop 0
	v_lshl_add_u64 v[102:103], v[102:103], 1, s[54:55]
	s_waitcnt vmcnt(27)
	v_pk_add_f32 v[94:95], v[94:95], v[194:195]
	v_pk_add_f32 v[92:93], v[92:93], v[192:193]
	v_cvt_pk_bf16_f32 v99, v94, v95
	v_cvt_pk_bf16_f32 v98, v92, v93
	global_store_dwordx4 v[104:105], v[92:95], off
	global_store_dwordx2 v[102:103], v[98:99], off
	s_nop 0
	v_mul_f32_e32 v93, v93, v93
	v_mul_f32_e32 v95, v95, v95
	v_fmac_f32_e32 v93, v92, v92
	v_fmac_f32_e32 v95, v94, v94
	v_add_f32_e32 v92, v93, v95
	s_waitcnt vmcnt(28)
	v_pk_add_f32 v[90:91], v[90:91], v[198:199]
	v_pk_add_f32 v[88:89], v[88:89], v[196:197]
	v_cvt_pk_bf16_f32 v99, v90, v91
	v_cvt_pk_bf16_f32 v98, v88, v89
	global_store_dwordx4 v[104:105], v[88:91], off offset:64
	global_store_dwordx2 v[102:103], v[98:99], off offset:32
	s_nop 0
	v_mul_f32_e32 v89, v89, v89
	v_mul_f32_e32 v91, v91, v91
	v_fmac_f32_e32 v89, v88, v88
	v_fmac_f32_e32 v91, v90, v90
	v_add_f32_e32 v88, v89, v91
	v_add_f32_e32 v88, v92, v88
	s_waitcnt vmcnt(29)
	v_pk_add_f32 v[86:87], v[86:87], v[202:203]
	v_pk_add_f32 v[84:85], v[84:85], v[200:201]
	v_cvt_pk_bf16_f32 v99, v86, v87
	v_cvt_pk_bf16_f32 v98, v84, v85
	global_store_dwordx4 v[104:105], v[84:87], off offset:512
	global_store_dwordx2 v[102:103], v[98:99], off offset:256
	s_nop 0
	v_mul_f32_e32 v85, v85, v85
	v_mul_f32_e32 v87, v87, v87
	v_fmac_f32_e32 v85, v84, v84
	v_fmac_f32_e32 v87, v86, v86
	v_add_f32_e32 v84, v85, v87
	v_add_f32_e32 v86, v88, v84
	s_waitcnt vmcnt(30)
	v_pk_add_f32 v[84:85], v[82:83], v[206:207]
	v_pk_add_f32 v[82:83], v[80:81], v[204:205]
	v_add_u32_e32 v209, 0x120000, v208
	global_load_dwordx4 v[192:195], v209, s[18:19]
	global_load_dwordx4 v[196:199], v209, s[18:19] offset:64
	global_load_dwordx4 v[200:203], v209, s[18:19] offset:512
	global_load_dwordx4 v[204:207], v209, s[18:19] offset:576
	v_mul_f32_e32 v81, v85, v85
	v_mul_f32_e32 v80, v83, v83
	v_fmac_f32_e32 v80, v82, v82
	v_fmac_f32_e32 v81, v84, v84
	v_add_f32_e32 v80, v80, v81
	v_add_f32_e32 v80, v86, v80
	ds_bpermute_b32 v81, v147, v80
	global_store_dwordx4 v[104:105], v[82:85], off offset:576
	s_waitcnt lgkmcnt(0)
	v_add_f32_e32 v80, v80, v81
	ds_bpermute_b32 v81, v148, v80
	v_cvt_pk_bf16_f32 v82, v82, v83
	v_cvt_pk_bf16_f32 v83, v84, v85
	global_store_dwordx2 v[102:103], v[82:83], off offset:288
	s_and_saveexec_b64 s[72:73], s[14:15]
	s_cbranch_execz .LBB0_1906
	v_lshlrev_b64 v[82:83], 7, v[96:97]
	v_lshl_add_u64 v[82:83], s[52:53], 0, v[82:83]
	v_lshl_add_u64 v[82:83], s[70:71], 2, v[82:83]
	s_lshl_b32 s20, s3, 2
	v_lshl_add_u64 v[82:83], v[82:83], 0, s[20:21]
	s_waitcnt lgkmcnt(0)
	v_add_f32_e32 v80, v80, v81
	global_store_dword v[82:83], v80, off
.LBB0_1906:
	s_or_b64 exec, exec, s[72:73]
	v_or_b32_e32 v80, 48, v142
	s_waitcnt lgkmcnt(0)
	v_ashrrev_i32_e32 v81, 31, v80
	v_lshlrev_b64 v[82:83], 11, v[80:81]
	v_lshl_add_u64 v[86:87], v[82:83], 0, v[140:141]
	v_lshl_add_u64 v[88:89], v[86:87], 2, s[18:19]
	s_nop 0
	v_lshl_add_u64 v[86:87], v[86:87], 1, s[54:55]
	s_waitcnt vmcnt(29)
	v_pk_add_f32 v[78:79], v[78:79], v[162:163]
	v_pk_add_f32 v[76:77], v[76:77], v[160:161]
	v_cvt_pk_bf16_f32 v83, v78, v79
	v_cvt_pk_bf16_f32 v82, v76, v77
	global_store_dwordx4 v[88:89], v[76:79], off
	global_store_dwordx2 v[86:87], v[82:83], off
	s_nop 0
	v_mul_f32_e32 v77, v77, v77
	v_mul_f32_e32 v79, v79, v79
	v_fmac_f32_e32 v77, v76, v76
	v_fmac_f32_e32 v79, v78, v78
	v_add_f32_e32 v76, v77, v79
	s_waitcnt vmcnt(30)
	v_pk_add_f32 v[74:75], v[74:75], v[166:167]
	v_pk_add_f32 v[72:73], v[72:73], v[164:165]
	v_cvt_pk_bf16_f32 v83, v74, v75
	v_cvt_pk_bf16_f32 v82, v72, v73
	global_store_dwordx4 v[88:89], v[72:75], off offset:64
	global_store_dwordx2 v[86:87], v[82:83], off offset:32
	s_nop 0
	v_mul_f32_e32 v73, v73, v73
	v_mul_f32_e32 v75, v75, v75
	v_fmac_f32_e32 v73, v72, v72
	v_fmac_f32_e32 v75, v74, v74
	v_add_f32_e32 v72, v73, v75
	v_add_f32_e32 v72, v76, v72
	s_waitcnt vmcnt(31)
	v_pk_add_f32 v[70:71], v[70:71], v[170:171]
	v_pk_add_f32 v[68:69], v[68:69], v[168:169]
	v_cvt_pk_bf16_f32 v83, v70, v71
	v_cvt_pk_bf16_f32 v82, v68, v69
	global_store_dwordx4 v[88:89], v[68:71], off offset:512
	global_store_dwordx2 v[86:87], v[82:83], off offset:256
	s_nop 0
	v_mul_f32_e32 v69, v69, v69
	v_mul_f32_e32 v71, v71, v71
	v_fmac_f32_e32 v69, v68, v68
	v_fmac_f32_e32 v71, v70, v70
	v_add_f32_e32 v68, v69, v71
	v_add_f32_e32 v70, v72, v68
	s_waitcnt vmcnt(32)
	v_pk_add_f32 v[68:69], v[66:67], v[174:175]
	v_pk_add_f32 v[66:67], v[64:65], v[172:173]
	v_add_u32_e32 v209, 0x140000, v208
	global_load_dwordx4 v[160:163], v209, s[18:19]
	global_load_dwordx4 v[164:167], v209, s[18:19] offset:64
	global_load_dwordx4 v[168:171], v209, s[18:19] offset:512
	global_load_dwordx4 v[172:175], v209, s[18:19] offset:576
	v_mul_f32_e32 v65, v69, v69
	v_mul_f32_e32 v64, v67, v67
	v_fmac_f32_e32 v64, v66, v66
	v_fmac_f32_e32 v65, v68, v68
	v_add_f32_e32 v64, v64, v65
	v_add_f32_e32 v64, v70, v64
	ds_bpermute_b32 v65, v147, v64
	global_store_dwordx4 v[88:89], v[66:69], off offset:576
	s_waitcnt lgkmcnt(0)
	v_add_f32_e32 v64, v64, v65
	ds_bpermute_b32 v65, v148, v64
	v_cvt_pk_bf16_f32 v66, v66, v67
	v_cvt_pk_bf16_f32 v67, v68, v69
	global_store_dwordx2 v[86:87], v[66:67], off offset:288
	s_and_saveexec_b64 s[72:73], s[14:15]
	s_cbranch_execz .LBB0_1908
	v_lshlrev_b64 v[66:67], 7, v[80:81]
	v_lshl_add_u64 v[66:67], s[52:53], 0, v[66:67]
	v_lshl_add_u64 v[66:67], s[70:71], 2, v[66:67]
	s_lshl_b32 s20, s3, 2
	v_lshl_add_u64 v[66:67], v[66:67], 0, s[20:21]
	s_waitcnt lgkmcnt(0)
	v_add_f32_e32 v64, v64, v65
	global_store_dword v[66:67], v64, off
.LBB0_1908:
	s_or_b64 exec, exec, s[72:73]
	v_add_u32_e32 v64, 0x80, v142
	s_waitcnt lgkmcnt(0)
	v_ashrrev_i32_e32 v65, 31, v64
	v_lshlrev_b64 v[66:67], 11, v[64:65]
	v_lshl_add_u64 v[70:71], v[66:67], 0, v[140:141]
	v_lshl_add_u64 v[72:73], v[70:71], 2, s[18:19]
	s_nop 0
	v_lshl_add_u64 v[70:71], v[70:71], 1, s[54:55]
	s_waitcnt vmcnt(29)
	v_pk_add_f32 v[62:63], v[62:63], v[178:179]
	v_pk_add_f32 v[60:61], v[60:61], v[176:177]
	v_cvt_pk_bf16_f32 v67, v62, v63
	v_cvt_pk_bf16_f32 v66, v60, v61
	global_store_dwordx4 v[72:73], v[60:63], off
	global_store_dwordx2 v[70:71], v[66:67], off
	s_nop 0
	v_mul_f32_e32 v61, v61, v61
	v_mul_f32_e32 v63, v63, v63
	v_fmac_f32_e32 v61, v60, v60
	v_fmac_f32_e32 v63, v62, v62
	v_add_f32_e32 v60, v61, v63
	s_waitcnt vmcnt(30)
	v_pk_add_f32 v[58:59], v[58:59], v[182:183]
	v_pk_add_f32 v[56:57], v[56:57], v[180:181]
	v_cvt_pk_bf16_f32 v67, v58, v59
	v_cvt_pk_bf16_f32 v66, v56, v57
	global_store_dwordx4 v[72:73], v[56:59], off offset:64
	global_store_dwordx2 v[70:71], v[66:67], off offset:32
	s_nop 0
	v_mul_f32_e32 v57, v57, v57
	v_mul_f32_e32 v59, v59, v59
	v_fmac_f32_e32 v57, v56, v56
	v_fmac_f32_e32 v59, v58, v58
	v_add_f32_e32 v56, v57, v59
	v_add_f32_e32 v56, v60, v56
	s_waitcnt vmcnt(31)
	v_pk_add_f32 v[54:55], v[54:55], v[186:187]
	v_pk_add_f32 v[52:53], v[52:53], v[184:185]
	v_cvt_pk_bf16_f32 v67, v54, v55
	v_cvt_pk_bf16_f32 v66, v52, v53
	global_store_dwordx4 v[72:73], v[52:55], off offset:512
	global_store_dwordx2 v[70:71], v[66:67], off offset:256
	s_nop 0
	v_mul_f32_e32 v53, v53, v53
	v_mul_f32_e32 v55, v55, v55
	v_fmac_f32_e32 v53, v52, v52
	v_fmac_f32_e32 v55, v54, v54
	v_add_f32_e32 v52, v53, v55
	v_add_f32_e32 v54, v56, v52
	s_waitcnt vmcnt(32)
	v_pk_add_f32 v[52:53], v[50:51], v[190:191]
	v_pk_add_f32 v[50:51], v[48:49], v[188:189]
	v_add_u32_e32 v209, 0x160000, v208
	global_load_dwordx4 v[176:179], v209, s[18:19]
	global_load_dwordx4 v[180:183], v209, s[18:19] offset:64
	global_load_dwordx4 v[184:187], v209, s[18:19] offset:512
	global_load_dwordx4 v[188:191], v209, s[18:19] offset:576
	v_mul_f32_e32 v49, v53, v53
	v_mul_f32_e32 v48, v51, v51
	v_fmac_f32_e32 v48, v50, v50
	v_fmac_f32_e32 v49, v52, v52
	v_add_f32_e32 v48, v48, v49
	v_add_f32_e32 v48, v54, v48
	ds_bpermute_b32 v49, v147, v48
	global_store_dwordx4 v[72:73], v[50:53], off offset:576
	s_waitcnt lgkmcnt(0)
	v_add_f32_e32 v48, v48, v49
	ds_bpermute_b32 v49, v148, v48
	v_cvt_pk_bf16_f32 v50, v50, v51
	v_cvt_pk_bf16_f32 v51, v52, v53
	global_store_dwordx2 v[70:71], v[50:51], off offset:288
	s_and_saveexec_b64 s[72:73], s[14:15]
	s_cbranch_execz .LBB0_1910
	v_lshlrev_b64 v[50:51], 7, v[64:65]
	v_lshl_add_u64 v[50:51], s[52:53], 0, v[50:51]
	v_lshl_add_u64 v[50:51], s[70:71], 2, v[50:51]
	s_lshl_b32 s20, s3, 2
	v_lshl_add_u64 v[50:51], v[50:51], 0, s[20:21]
	s_waitcnt lgkmcnt(0)
	v_add_f32_e32 v48, v48, v49
	global_store_dword v[50:51], v48, off
.LBB0_1910:
	s_or_b64 exec, exec, s[72:73]
	v_add_u32_e32 v48, 0x90, v142
	s_waitcnt lgkmcnt(0)
	v_ashrrev_i32_e32 v49, 31, v48
	v_lshlrev_b64 v[50:51], 11, v[48:49]
	v_lshl_add_u64 v[54:55], v[50:51], 0, v[140:141]
	v_lshl_add_u64 v[56:57], v[54:55], 2, s[18:19]
	s_nop 0
	v_lshl_add_u64 v[54:55], v[54:55], 1, s[54:55]
	s_waitcnt vmcnt(29)
	v_pk_add_f32 v[46:47], v[46:47], v[194:195]
	v_pk_add_f32 v[44:45], v[44:45], v[192:193]
	v_cvt_pk_bf16_f32 v51, v46, v47
	v_cvt_pk_bf16_f32 v50, v44, v45
	global_store_dwordx4 v[56:57], v[44:47], off
	global_store_dwordx2 v[54:55], v[50:51], off
	s_nop 0
	v_mul_f32_e32 v45, v45, v45
	v_mul_f32_e32 v47, v47, v47
	v_fmac_f32_e32 v45, v44, v44
	v_fmac_f32_e32 v47, v46, v46
	v_add_f32_e32 v44, v45, v47
	s_waitcnt vmcnt(30)
	v_pk_add_f32 v[42:43], v[42:43], v[198:199]
	v_pk_add_f32 v[40:41], v[40:41], v[196:197]
	v_cvt_pk_bf16_f32 v51, v42, v43
	v_cvt_pk_bf16_f32 v50, v40, v41
	global_store_dwordx4 v[56:57], v[40:43], off offset:64
	global_store_dwordx2 v[54:55], v[50:51], off offset:32
	s_nop 0
	v_mul_f32_e32 v41, v41, v41
	v_mul_f32_e32 v43, v43, v43
	v_fmac_f32_e32 v41, v40, v40
	v_fmac_f32_e32 v43, v42, v42
	v_add_f32_e32 v40, v41, v43
	v_add_f32_e32 v40, v44, v40
	s_waitcnt vmcnt(31)
	v_pk_add_f32 v[38:39], v[38:39], v[202:203]
	v_pk_add_f32 v[36:37], v[36:37], v[200:201]
	v_cvt_pk_bf16_f32 v51, v38, v39
	v_cvt_pk_bf16_f32 v50, v36, v37
	global_store_dwordx4 v[56:57], v[36:39], off offset:512
	global_store_dwordx2 v[54:55], v[50:51], off offset:256
	s_nop 0
	v_mul_f32_e32 v37, v37, v37
	v_mul_f32_e32 v39, v39, v39
	v_fmac_f32_e32 v37, v36, v36
	v_fmac_f32_e32 v39, v38, v38
	v_add_f32_e32 v36, v37, v39
	v_add_f32_e32 v38, v40, v36
	s_waitcnt vmcnt(32)
	v_pk_add_f32 v[36:37], v[34:35], v[206:207]
	v_pk_add_f32 v[34:35], v[32:33], v[204:205]
	v_mul_f32_e32 v33, v37, v37
	v_mul_f32_e32 v32, v35, v35
	v_fmac_f32_e32 v32, v34, v34
	v_fmac_f32_e32 v33, v36, v36
	v_add_f32_e32 v32, v32, v33
	v_add_f32_e32 v32, v38, v32
	ds_bpermute_b32 v33, v147, v32
	global_store_dwordx4 v[56:57], v[34:37], off offset:576
	s_waitcnt lgkmcnt(0)
	v_add_f32_e32 v32, v32, v33
	ds_bpermute_b32 v33, v148, v32
	v_cvt_pk_bf16_f32 v34, v34, v35
	v_cvt_pk_bf16_f32 v35, v36, v37
	global_store_dwordx2 v[54:55], v[34:35], off offset:288
	s_and_saveexec_b64 s[72:73], s[14:15]
	s_cbranch_execz .LBB0_1912
	v_lshlrev_b64 v[34:35], 7, v[48:49]
	v_lshl_add_u64 v[34:35], s[52:53], 0, v[34:35]
	v_lshl_add_u64 v[34:35], s[70:71], 2, v[34:35]
	s_lshl_b32 s20, s3, 2
	v_lshl_add_u64 v[34:35], v[34:35], 0, s[20:21]
	s_waitcnt lgkmcnt(0)
	v_add_f32_e32 v32, v32, v33
	global_store_dword v[34:35], v32, off
.LBB0_1912:
	s_or_b64 exec, exec, s[72:73]
	v_add_u32_e32 v32, 0xa0, v142
	s_waitcnt lgkmcnt(0)
	v_ashrrev_i32_e32 v33, 31, v32
	v_lshlrev_b64 v[34:35], 11, v[32:33]
	v_lshl_add_u64 v[38:39], v[34:35], 0, v[140:141]
	v_lshl_add_u64 v[40:41], v[38:39], 2, s[18:19]
	s_nop 0
	v_lshl_add_u64 v[38:39], v[38:39], 1, s[54:55]
	s_waitcnt vmcnt(25)
	v_pk_add_f32 v[30:31], v[30:31], v[162:163]
	v_pk_add_f32 v[28:29], v[28:29], v[160:161]
	v_cvt_pk_bf16_f32 v35, v30, v31
	v_cvt_pk_bf16_f32 v34, v28, v29
	global_store_dwordx4 v[40:41], v[28:31], off
	global_store_dwordx2 v[38:39], v[34:35], off
	s_nop 0
	v_mul_f32_e32 v29, v29, v29
	v_mul_f32_e32 v31, v31, v31
	v_fmac_f32_e32 v29, v28, v28
	v_fmac_f32_e32 v31, v30, v30
	v_add_f32_e32 v28, v29, v31
	s_waitcnt vmcnt(26)
	v_pk_add_f32 v[26:27], v[26:27], v[166:167]
	v_pk_add_f32 v[24:25], v[24:25], v[164:165]
	v_cvt_pk_bf16_f32 v35, v26, v27
	v_cvt_pk_bf16_f32 v34, v24, v25
	global_store_dwordx4 v[40:41], v[24:27], off offset:64
	global_store_dwordx2 v[38:39], v[34:35], off offset:32
	s_nop 0
	v_mul_f32_e32 v25, v25, v25
	v_mul_f32_e32 v27, v27, v27
	v_fmac_f32_e32 v25, v24, v24
	v_fmac_f32_e32 v27, v26, v26
	v_add_f32_e32 v24, v25, v27
	v_add_f32_e32 v24, v28, v24
	s_waitcnt vmcnt(27)
	v_pk_add_f32 v[22:23], v[22:23], v[170:171]
	v_pk_add_f32 v[20:21], v[20:21], v[168:169]
	v_cvt_pk_bf16_f32 v35, v22, v23
	v_cvt_pk_bf16_f32 v34, v20, v21
	global_store_dwordx4 v[40:41], v[20:23], off offset:512
	global_store_dwordx2 v[38:39], v[34:35], off offset:256
	s_nop 0
	v_mul_f32_e32 v21, v21, v21
	v_mul_f32_e32 v23, v23, v23
	v_fmac_f32_e32 v21, v20, v20
	v_fmac_f32_e32 v23, v22, v22
	v_add_f32_e32 v20, v21, v23
	v_add_f32_e32 v22, v24, v20
	s_waitcnt vmcnt(28)
	v_pk_add_f32 v[20:21], v[18:19], v[174:175]
	v_pk_add_f32 v[18:19], v[16:17], v[172:173]
	v_mul_f32_e32 v17, v21, v21
	v_mul_f32_e32 v16, v19, v19
	v_fmac_f32_e32 v16, v18, v18
	v_fmac_f32_e32 v17, v20, v20
	v_add_f32_e32 v16, v16, v17
	v_add_f32_e32 v16, v22, v16
	ds_bpermute_b32 v17, v147, v16
	global_store_dwordx4 v[40:41], v[18:21], off offset:576
	s_waitcnt lgkmcnt(0)
	v_add_f32_e32 v16, v16, v17
	ds_bpermute_b32 v17, v148, v16
	v_cvt_pk_bf16_f32 v18, v18, v19
	v_cvt_pk_bf16_f32 v19, v20, v21
	global_store_dwordx2 v[38:39], v[18:19], off offset:288
	s_and_saveexec_b64 s[72:73], s[14:15]
	s_cbranch_execz .LBB0_1914
	v_lshlrev_b64 v[18:19], 7, v[32:33]
	v_lshl_add_u64 v[18:19], s[52:53], 0, v[18:19]
	v_lshl_add_u64 v[18:19], s[70:71], 2, v[18:19]
	s_lshl_b32 s20, s3, 2
	v_lshl_add_u64 v[18:19], v[18:19], 0, s[20:21]
	s_waitcnt lgkmcnt(0)
	v_add_f32_e32 v16, v16, v17
	global_store_dword v[18:19], v16, off
.LBB0_1914:
	s_or_b64 exec, exec, s[72:73]
	v_add_u32_e32 v16, 0xb0, v142
	s_waitcnt lgkmcnt(0)
	v_ashrrev_i32_e32 v17, 31, v16
	v_lshlrev_b64 v[18:19], 11, v[16:17]
	v_lshl_add_u64 v[22:23], v[18:19], 0, v[140:141]
	v_lshl_add_u64 v[24:25], v[22:23], 2, s[18:19]
	s_nop 0
	v_lshl_add_u64 v[22:23], v[22:23], 1, s[54:55]
	s_waitcnt vmcnt(21)
	v_pk_add_f32 v[14:15], v[14:15], v[178:179]
	v_pk_add_f32 v[12:13], v[12:13], v[176:177]
	v_cvt_pk_bf16_f32 v19, v14, v15
	v_cvt_pk_bf16_f32 v18, v12, v13
	global_store_dwordx4 v[24:25], v[12:15], off
	global_store_dwordx2 v[22:23], v[18:19], off
	s_nop 0
	v_mul_f32_e32 v13, v13, v13
	v_mul_f32_e32 v15, v15, v15
	v_fmac_f32_e32 v13, v12, v12
	v_fmac_f32_e32 v15, v14, v14
	v_add_f32_e32 v12, v13, v15
	s_waitcnt vmcnt(22)
	v_pk_add_f32 v[10:11], v[10:11], v[182:183]
	v_pk_add_f32 v[8:9], v[8:9], v[180:181]
	v_cvt_pk_bf16_f32 v19, v10, v11
	v_cvt_pk_bf16_f32 v18, v8, v9
	global_store_dwordx4 v[24:25], v[8:11], off offset:64
	global_store_dwordx2 v[22:23], v[18:19], off offset:32
	s_nop 0
	v_mul_f32_e32 v9, v9, v9
	v_mul_f32_e32 v11, v11, v11
	v_fmac_f32_e32 v9, v8, v8
	v_fmac_f32_e32 v11, v10, v10
	v_add_f32_e32 v8, v9, v11
	v_add_f32_e32 v8, v12, v8
	s_waitcnt vmcnt(23)
	v_pk_add_f32 v[6:7], v[6:7], v[186:187]
	v_pk_add_f32 v[4:5], v[4:5], v[184:185]
	v_cvt_pk_bf16_f32 v19, v6, v7
	v_cvt_pk_bf16_f32 v18, v4, v5
	global_store_dwordx4 v[24:25], v[4:7], off offset:512
	global_store_dwordx2 v[22:23], v[18:19], off offset:256
	s_nop 0
	v_mul_f32_e32 v5, v5, v5
	v_mul_f32_e32 v7, v7, v7
	v_fmac_f32_e32 v5, v4, v4
	v_fmac_f32_e32 v7, v6, v6
	v_add_f32_e32 v4, v5, v7
	v_add_f32_e32 v6, v8, v4
	s_waitcnt vmcnt(24)
	v_pk_add_f32 v[4:5], v[2:3], v[190:191]
	v_pk_add_f32 v[2:3], v[0:1], v[188:189]
	v_mul_f32_e32 v1, v5, v5
	v_mul_f32_e32 v0, v3, v3
	v_fmac_f32_e32 v0, v2, v2
	v_fmac_f32_e32 v1, v4, v4
	v_add_f32_e32 v0, v0, v1
	v_add_f32_e32 v0, v6, v0
	ds_bpermute_b32 v1, v147, v0
	global_store_dwordx4 v[24:25], v[2:5], off offset:576
	s_waitcnt lgkmcnt(0)
	v_add_f32_e32 v0, v0, v1
	ds_bpermute_b32 v1, v148, v0
	v_cvt_pk_bf16_f32 v2, v2, v3
	v_cvt_pk_bf16_f32 v3, v4, v5
	global_store_dwordx2 v[22:23], v[2:3], off offset:288
	s_and_saveexec_b64 s[72:73], s[14:15]
	s_cbranch_execz .LBB0_1916
	v_lshlrev_b64 v[2:3], 7, v[16:17]
	v_lshl_add_u64 v[2:3], s[52:53], 0, v[2:3]
	v_lshl_add_u64 v[2:3], s[70:71], 2, v[2:3]
	s_lshl_b32 s20, s3, 2
	v_lshl_add_u64 v[2:3], v[2:3], 0, s[20:21]
	s_waitcnt lgkmcnt(0)
	v_add_f32_e32 v0, v0, v1
	global_store_dword v[2:3], v0, off

.LBB0_2716:
	v_lshl_add_u32 v142, s56, 8, v144
	v_lshl_add_u32 v140, s18, 8, v146
	v_lshl_add_u32 v208, v142, 11, v140
	v_lshlrev_b32_e32 v208, 2, v208
	global_load_dwordx4 v[160:163], v208, s[16:17]
	global_load_dwordx4 v[164:167], v208, s[16:17] offset:64
	global_load_dwordx4 v[168:171], v208, s[16:17] offset:512
	global_load_dwordx4 v[172:175], v208, s[16:17] offset:576
	v_add_u32_e32 v209, 0x20000, v208
	global_load_dwordx4 v[176:179], v209, s[16:17]
	global_load_dwordx4 v[180:183], v209, s[16:17] offset:64
	global_load_dwordx4 v[184:187], v209, s[16:17] offset:512
	global_load_dwordx4 v[188:191], v209, s[16:17] offset:576
	v_add_u32_e32 v209, 0x40000, v208
	global_load_dwordx4 v[192:195], v209, s[16:17]
	global_load_dwordx4 v[196:199], v209, s[16:17] offset:64
	global_load_dwordx4 v[200:203], v209, s[16:17] offset:512
	global_load_dwordx4 v[204:207], v209, s[16:17] offset:576
	v_ashrrev_i32_e32 v143, 31, v142
	v_ashrrev_i32_e32 v141, 31, v140
	v_lshlrev_b64 v[152:153], 11, v[142:143]
	v_lshl_add_u64 v[156:157], v[152:153], 0, v[140:141]
	v_lshl_add_u64 v[158:159], v[156:157], 2, s[16:17]
	s_nop 0
	v_lshl_add_u64 v[156:157], v[156:157], 1, s[54:55]
	s_lshl_b32 s56, s18, 2
	s_ashr_i32 s57, s56, 31
	s_waitcnt vmcnt(11)
	v_pk_add_f32 v[126:127], v[126:127], v[162:163]
	v_pk_add_f32 v[124:125], v[124:125], v[160:161]
	v_cvt_pk_bf16_f32 v153, v126, v127
	v_cvt_pk_bf16_f32 v152, v124, v125
	global_store_dwordx4 v[158:159], v[124:127], off
	global_store_dwordx2 v[156:157], v[152:153], off
	s_nop 0
	v_mul_f32_e32 v125, v125, v125
	v_mul_f32_e32 v127, v127, v127
	v_fmac_f32_e32 v125, v124, v124
	v_fmac_f32_e32 v127, v126, v126
	v_add_f32_e32 v124, v125, v127
	s_waitcnt vmcnt(12)
	v_pk_add_f32 v[122:123], v[122:123], v[166:167]
	v_pk_add_f32 v[120:121], v[120:121], v[164:165]
	v_cvt_pk_bf16_f32 v153, v122, v123
	v_cvt_pk_bf16_f32 v152, v120, v121
	global_store_dwordx4 v[158:159], v[120:123], off offset:64
	global_store_dwordx2 v[156:157], v[152:153], off offset:32
	s_nop 0
	v_mul_f32_e32 v121, v121, v121
	v_mul_f32_e32 v123, v123, v123
	v_fmac_f32_e32 v121, v120, v120
	v_fmac_f32_e32 v123, v122, v122
	v_add_f32_e32 v120, v121, v123
	v_add_f32_e32 v120, v124, v120
	s_waitcnt vmcnt(13)
	v_pk_add_f32 v[118:119], v[118:119], v[170:171]
	v_pk_add_f32 v[116:117], v[116:117], v[168:169]
	v_cvt_pk_bf16_f32 v153, v118, v119
	v_cvt_pk_bf16_f32 v152, v116, v117
	global_store_dwordx4 v[158:159], v[116:119], off offset:512
	global_store_dwordx2 v[156:157], v[152:153], off offset:256
	s_nop 0
	v_mul_f32_e32 v117, v117, v117
	v_mul_f32_e32 v119, v119, v119
	v_fmac_f32_e32 v117, v116, v116
	v_fmac_f32_e32 v119, v118, v118
	v_add_f32_e32 v116, v117, v119
	v_add_f32_e32 v118, v120, v116
	s_waitcnt vmcnt(14)
	v_pk_add_f32 v[116:117], v[114:115], v[174:175]
	v_pk_add_f32 v[114:115], v[112:113], v[172:173]
	v_add_u32_e32 v209, 0x60000, v208
	global_load_dwordx4 v[160:163], v209, s[16:17]
	global_load_dwordx4 v[164:167], v209, s[16:17] offset:64
	global_load_dwordx4 v[168:171], v209, s[16:17] offset:512
	global_load_dwordx4 v[172:175], v209, s[16:17] offset:576
	v_mul_f32_e32 v113, v117, v117
	v_mul_f32_e32 v112, v115, v115
	v_fmac_f32_e32 v112, v114, v114
	v_fmac_f32_e32 v113, v116, v116
	v_add_f32_e32 v112, v112, v113
	v_add_f32_e32 v112, v118, v112
	ds_bpermute_b32 v113, v147, v112
	global_store_dwordx4 v[158:159], v[114:117], off offset:576
	s_waitcnt lgkmcnt(0)
	v_add_f32_e32 v112, v112, v113
	ds_bpermute_b32 v113, v148, v112
	v_cvt_pk_bf16_f32 v114, v114, v115
	v_cvt_pk_bf16_f32 v115, v116, v117
	global_store_dwordx2 v[156:157], v[114:115], off offset:288
	s_and_saveexec_b64 s[62:63], s[6:7]
	s_cbranch_execz .LBB0_2718
	v_lshlrev_b64 v[114:115], 7, v[142:143]
	v_lshl_add_u64 v[114:115], s[52:53], 0, v[114:115]
	v_lshl_add_u64 v[114:115], s[56:57], 2, v[114:115]
	s_lshl_b32 s18, s3, 2
	v_lshl_add_u64 v[114:115], v[114:115], 0, s[18:19]
	s_waitcnt lgkmcnt(0)
	v_add_f32_e32 v112, v112, v113
	global_store_dword v[114:115], v112, off
.LBB0_2718:
	s_or_b64 exec, exec, s[62:63]
	v_or_b32_e32 v112, 16, v142
	s_waitcnt lgkmcnt(0)
	v_ashrrev_i32_e32 v113, 31, v112
	v_lshlrev_b64 v[114:115], 11, v[112:113]
	v_lshl_add_u64 v[118:119], v[114:115], 0, v[140:141]
	v_lshl_add_u64 v[120:121], v[118:119], 2, s[16:17]
	s_nop 0
	v_lshl_add_u64 v[118:119], v[118:119], 1, s[54:55]
	s_waitcnt vmcnt(19)
	v_pk_add_f32 v[110:111], v[110:111], v[178:179]
	v_pk_add_f32 v[108:109], v[108:109], v[176:177]
	v_cvt_pk_bf16_f32 v115, v110, v111
	v_cvt_pk_bf16_f32 v114, v108, v109
	global_store_dwordx4 v[120:121], v[108:111], off
	global_store_dwordx2 v[118:119], v[114:115], off
	s_nop 0
	v_mul_f32_e32 v109, v109, v109
	v_mul_f32_e32 v111, v111, v111
	v_fmac_f32_e32 v109, v108, v108
	v_fmac_f32_e32 v111, v110, v110
	v_add_f32_e32 v108, v109, v111
	s_waitcnt vmcnt(20)
	v_pk_add_f32 v[106:107], v[106:107], v[182:183]
	v_pk_add_f32 v[104:105], v[104:105], v[180:181]
	v_cvt_pk_bf16_f32 v115, v106, v107
	v_cvt_pk_bf16_f32 v114, v104, v105
	global_store_dwordx4 v[120:121], v[104:107], off offset:64
	global_store_dwordx2 v[118:119], v[114:115], off offset:32
	s_nop 0
	v_mul_f32_e32 v105, v105, v105
	v_mul_f32_e32 v107, v107, v107
	v_fmac_f32_e32 v105, v104, v104
	v_fmac_f32_e32 v107, v106, v106
	v_add_f32_e32 v104, v105, v107
	v_add_f32_e32 v104, v108, v104
	s_waitcnt vmcnt(21)
	v_pk_add_f32 v[102:103], v[102:103], v[186:187]
	v_pk_add_f32 v[100:101], v[100:101], v[184:185]
	v_cvt_pk_bf16_f32 v115, v102, v103
	v_cvt_pk_bf16_f32 v114, v100, v101
	global_store_dwordx4 v[120:121], v[100:103], off offset:512
	global_store_dwordx2 v[118:119], v[114:115], off offset:256
	s_nop 0
	v_mul_f32_e32 v101, v101, v101
	v_mul_f32_e32 v103, v103, v103
	v_fmac_f32_e32 v101, v100, v100
	v_fmac_f32_e32 v103, v102, v102
	v_add_f32_e32 v100, v101, v103
	v_add_f32_e32 v102, v104, v100
	s_waitcnt vmcnt(22)
	v_pk_add_f32 v[100:101], v[98:99], v[190:191]
	v_pk_add_f32 v[98:99], v[96:97], v[188:189]
	v_add_u32_e32 v209, 0x100000, v208
	global_load_dwordx4 v[176:179], v209, s[16:17]
	global_load_dwordx4 v[180:183], v209, s[16:17] offset:64
	global_load_dwordx4 v[184:187], v209, s[16:17] offset:512
	global_load_dwordx4 v[188:191], v209, s[16:17] offset:576
	v_mul_f32_e32 v97, v101, v101
	v_mul_f32_e32 v96, v99, v99
	v_fmac_f32_e32 v96, v98, v98
	v_fmac_f32_e32 v97, v100, v100
	v_add_f32_e32 v96, v96, v97
	v_add_f32_e32 v96, v102, v96
	ds_bpermute_b32 v97, v147, v96
	global_store_dwordx4 v[120:121], v[98:101], off offset:576
	s_waitcnt lgkmcnt(0)
	v_add_f32_e32 v96, v96, v97
	ds_bpermute_b32 v97, v148, v96
	v_cvt_pk_bf16_f32 v98, v98, v99
	v_cvt_pk_bf16_f32 v99, v100, v101
	global_store_dwordx2 v[118:119], v[98:99], off offset:288
	s_and_saveexec_b64 s[62:63], s[6:7]
	s_cbranch_execz .LBB0_2720
	v_lshlrev_b64 v[98:99], 7, v[112:113]
	v_lshl_add_u64 v[98:99], s[52:53], 0, v[98:99]
	v_lshl_add_u64 v[98:99], s[56:57], 2, v[98:99]
	s_lshl_b32 s18, s3, 2
	v_lshl_add_u64 v[98:99], v[98:99], 0, s[18:19]
	s_waitcnt lgkmcnt(0)
	v_add_f32_e32 v96, v96, v97
	global_store_dword v[98:99], v96, off
.LBB0_2720:
	s_or_b64 exec, exec, s[62:63]
	v_or_b32_e32 v96, 32, v142
	s_waitcnt lgkmcnt(0)
	v_ashrrev_i32_e32 v97, 31, v96
	v_lshlrev_b64 v[98:99], 11, v[96:97]
	v_lshl_add_u64 v[102:103], v[98:99], 0, v[140:141]
	v_lshl_add_u64 v[104:105], v[102:103], 2, s[16:17]
	s_nop 0
	v_lshl_add_u64 v[102:103], v[102:103], 1, s[54:55]
	s_waitcnt vmcnt(27)
	v_pk_add_f32 v[94:95], v[94:95], v[194:195]
	v_pk_add_f32 v[92:93], v[92:93], v[192:193]
	v_cvt_pk_bf16_f32 v99, v94, v95
	v_cvt_pk_bf16_f32 v98, v92, v93
	global_store_dwordx4 v[104:105], v[92:95], off
	global_store_dwordx2 v[102:103], v[98:99], off
	s_nop 0
	v_mul_f32_e32 v93, v93, v93
	v_mul_f32_e32 v95, v95, v95
	v_fmac_f32_e32 v93, v92, v92
	v_fmac_f32_e32 v95, v94, v94
	v_add_f32_e32 v92, v93, v95
	s_waitcnt vmcnt(28)
	v_pk_add_f32 v[90:91], v[90:91], v[198:199]
	v_pk_add_f32 v[88:89], v[88:89], v[196:197]
	v_cvt_pk_bf16_f32 v99, v90, v91
	v_cvt_pk_bf16_f32 v98, v88, v89
	global_store_dwordx4 v[104:105], v[88:91], off offset:64
	global_store_dwordx2 v[102:103], v[98:99], off offset:32
	s_nop 0
	v_mul_f32_e32 v89, v89, v89
	v_mul_f32_e32 v91, v91, v91
	v_fmac_f32_e32 v89, v88, v88
	v_fmac_f32_e32 v91, v90, v90
	v_add_f32_e32 v88, v89, v91
	v_add_f32_e32 v88, v92, v88
	s_waitcnt vmcnt(29)
	v_pk_add_f32 v[86:87], v[86:87], v[202:203]
	v_pk_add_f32 v[84:85], v[84:85], v[200:201]
	v_cvt_pk_bf16_f32 v99, v86, v87
	v_cvt_pk_bf16_f32 v98, v84, v85
	global_store_dwordx4 v[104:105], v[84:87], off offset:512
	global_store_dwordx2 v[102:103], v[98:99], off offset:256
	s_nop 0
	v_mul_f32_e32 v85, v85, v85
	v_mul_f32_e32 v87, v87, v87
	v_fmac_f32_e32 v85, v84, v84
	v_fmac_f32_e32 v87, v86, v86
	v_add_f32_e32 v84, v85, v87
	v_add_f32_e32 v86, v88, v84
	s_waitcnt vmcnt(30)
	v_pk_add_f32 v[84:85], v[82:83], v[206:207]
	v_pk_add_f32 v[82:83], v[80:81], v[204:205]
	v_add_u32_e32 v209, 0x120000, v208
	global_load_dwordx4 v[192:195], v209, s[16:17]
	global_load_dwordx4 v[196:199], v209, s[16:17] offset:64
	global_load_dwordx4 v[200:203], v209, s[16:17] offset:512
	global_load_dwordx4 v[204:207], v209, s[16:17] offset:576
	v_mul_f32_e32 v81, v85, v85
	v_mul_f32_e32 v80, v83, v83
	v_fmac_f32_e32 v80, v82, v82
	v_fmac_f32_e32 v81, v84, v84
	v_add_f32_e32 v80, v80, v81
	v_add_f32_e32 v80, v86, v80
	ds_bpermute_b32 v81, v147, v80
	global_store_dwordx4 v[104:105], v[82:85], off offset:576
	s_waitcnt lgkmcnt(0)
	v_add_f32_e32 v80, v80, v81
	ds_bpermute_b32 v81, v148, v80
	v_cvt_pk_bf16_f32 v82, v82, v83
	v_cvt_pk_bf16_f32 v83, v84, v85
	global_store_dwordx2 v[102:103], v[82:83], off offset:288
	s_and_saveexec_b64 s[62:63], s[6:7]
	s_cbranch_execz .LBB0_2722
	v_lshlrev_b64 v[82:83], 7, v[96:97]
	v_lshl_add_u64 v[82:83], s[52:53], 0, v[82:83]
	v_lshl_add_u64 v[82:83], s[56:57], 2, v[82:83]
	s_lshl_b32 s18, s3, 2
	v_lshl_add_u64 v[82:83], v[82:83], 0, s[18:19]
	s_waitcnt lgkmcnt(0)
	v_add_f32_e32 v80, v80, v81
	global_store_dword v[82:83], v80, off
.LBB0_2722:
	s_or_b64 exec, exec, s[62:63]
	v_or_b32_e32 v80, 48, v142
	s_waitcnt lgkmcnt(0)
	v_ashrrev_i32_e32 v81, 31, v80
	v_lshlrev_b64 v[82:83], 11, v[80:81]
	v_lshl_add_u64 v[86:87], v[82:83], 0, v[140:141]
	v_lshl_add_u64 v[88:89], v[86:87], 2, s[16:17]
	s_nop 0
	v_lshl_add_u64 v[86:87], v[86:87], 1, s[54:55]
	s_waitcnt vmcnt(29)
	v_pk_add_f32 v[78:79], v[78:79], v[162:163]
	v_pk_add_f32 v[76:77], v[76:77], v[160:161]
	v_cvt_pk_bf16_f32 v83, v78, v79
	v_cvt_pk_bf16_f32 v82, v76, v77
	global_store_dwordx4 v[88:89], v[76:79], off
	global_store_dwordx2 v[86:87], v[82:83], off
	s_nop 0
	v_mul_f32_e32 v77, v77, v77
	v_mul_f32_e32 v79, v79, v79
	v_fmac_f32_e32 v77, v76, v76
	v_fmac_f32_e32 v79, v78, v78
	v_add_f32_e32 v76, v77, v79
	s_waitcnt vmcnt(30)
	v_pk_add_f32 v[74:75], v[74:75], v[166:167]
	v_pk_add_f32 v[72:73], v[72:73], v[164:165]
	v_cvt_pk_bf16_f32 v83, v74, v75
	v_cvt_pk_bf16_f32 v82, v72, v73
	global_store_dwordx4 v[88:89], v[72:75], off offset:64
	global_store_dwordx2 v[86:87], v[82:83], off offset:32
	s_nop 0
	v_mul_f32_e32 v73, v73, v73
	v_mul_f32_e32 v75, v75, v75
	v_fmac_f32_e32 v73, v72, v72
	v_fmac_f32_e32 v75, v74, v74
	v_add_f32_e32 v72, v73, v75
	v_add_f32_e32 v72, v76, v72
	s_waitcnt vmcnt(31)
	v_pk_add_f32 v[70:71], v[70:71], v[170:171]
	v_pk_add_f32 v[68:69], v[68:69], v[168:169]
	v_cvt_pk_bf16_f32 v83, v70, v71
	v_cvt_pk_bf16_f32 v82, v68, v69
	global_store_dwordx4 v[88:89], v[68:71], off offset:512
	global_store_dwordx2 v[86:87], v[82:83], off offset:256
	s_nop 0
	v_mul_f32_e32 v69, v69, v69
	v_mul_f32_e32 v71, v71, v71
	v_fmac_f32_e32 v69, v68, v68
	v_fmac_f32_e32 v71, v70, v70
	v_add_f32_e32 v68, v69, v71
	v_add_f32_e32 v70, v72, v68
	s_waitcnt vmcnt(32)
	v_pk_add_f32 v[68:69], v[66:67], v[174:175]
	v_pk_add_f32 v[66:67], v[64:65], v[172:173]
	v_add_u32_e32 v209, 0x140000, v208
	global_load_dwordx4 v[160:163], v209, s[16:17]
	global_load_dwordx4 v[164:167], v209, s[16:17] offset:64
	global_load_dwordx4 v[168:171], v209, s[16:17] offset:512
	global_load_dwordx4 v[172:175], v209, s[16:17] offset:576
	v_mul_f32_e32 v65, v69, v69
	v_mul_f32_e32 v64, v67, v67
	v_fmac_f32_e32 v64, v66, v66
	v_fmac_f32_e32 v65, v68, v68
	v_add_f32_e32 v64, v64, v65
	v_add_f32_e32 v64, v70, v64
	ds_bpermute_b32 v65, v147, v64
	global_store_dwordx4 v[88:89], v[66:69], off offset:576
	s_waitcnt lgkmcnt(0)
	v_add_f32_e32 v64, v64, v65
	ds_bpermute_b32 v65, v148, v64
	v_cvt_pk_bf16_f32 v66, v66, v67
	v_cvt_pk_bf16_f32 v67, v68, v69
	global_store_dwordx2 v[86:87], v[66:67], off offset:288
	s_and_saveexec_b64 s[62:63], s[6:7]
	s_cbranch_execz .LBB0_2724
	v_lshlrev_b64 v[66:67], 7, v[80:81]
	v_lshl_add_u64 v[66:67], s[52:53], 0, v[66:67]
	v_lshl_add_u64 v[66:67], s[56:57], 2, v[66:67]
	s_lshl_b32 s18, s3, 2
	v_lshl_add_u64 v[66:67], v[66:67], 0, s[18:19]
	s_waitcnt lgkmcnt(0)
	v_add_f32_e32 v64, v64, v65
	global_store_dword v[66:67], v64, off
.LBB0_2724:
	s_or_b64 exec, exec, s[62:63]
	v_add_u32_e32 v64, 0x80, v142
	s_waitcnt lgkmcnt(0)
	v_ashrrev_i32_e32 v65, 31, v64
	v_lshlrev_b64 v[66:67], 11, v[64:65]
	v_lshl_add_u64 v[70:71], v[66:67], 0, v[140:141]
	v_lshl_add_u64 v[72:73], v[70:71], 2, s[16:17]
	s_nop 0
	v_lshl_add_u64 v[70:71], v[70:71], 1, s[54:55]
	s_waitcnt vmcnt(29)
	v_pk_add_f32 v[62:63], v[62:63], v[178:179]
	v_pk_add_f32 v[60:61], v[60:61], v[176:177]
	v_cvt_pk_bf16_f32 v67, v62, v63
	v_cvt_pk_bf16_f32 v66, v60, v61
	global_store_dwordx4 v[72:73], v[60:63], off
	global_store_dwordx2 v[70:71], v[66:67], off
	s_nop 0
	v_mul_f32_e32 v61, v61, v61
	v_mul_f32_e32 v63, v63, v63
	v_fmac_f32_e32 v61, v60, v60
	v_fmac_f32_e32 v63, v62, v62
	v_add_f32_e32 v60, v61, v63
	s_waitcnt vmcnt(30)
	v_pk_add_f32 v[58:59], v[58:59], v[182:183]
	v_pk_add_f32 v[56:57], v[56:57], v[180:181]
	v_cvt_pk_bf16_f32 v67, v58, v59
	v_cvt_pk_bf16_f32 v66, v56, v57
	global_store_dwordx4 v[72:73], v[56:59], off offset:64
	global_store_dwordx2 v[70:71], v[66:67], off offset:32
	s_nop 0
	v_mul_f32_e32 v57, v57, v57
	v_mul_f32_e32 v59, v59, v59
	v_fmac_f32_e32 v57, v56, v56
	v_fmac_f32_e32 v59, v58, v58
	v_add_f32_e32 v56, v57, v59
	v_add_f32_e32 v56, v60, v56
	s_waitcnt vmcnt(31)
	v_pk_add_f32 v[54:55], v[54:55], v[186:187]
	v_pk_add_f32 v[52:53], v[52:53], v[184:185]
	v_cvt_pk_bf16_f32 v67, v54, v55
	v_cvt_pk_bf16_f32 v66, v52, v53
	global_store_dwordx4 v[72:73], v[52:55], off offset:512
	global_store_dwordx2 v[70:71], v[66:67], off offset:256
	s_nop 0
	v_mul_f32_e32 v53, v53, v53
	v_mul_f32_e32 v55, v55, v55
	v_fmac_f32_e32 v53, v52, v52
	v_fmac_f32_e32 v55, v54, v54
	v_add_f32_e32 v52, v53, v55
	v_add_f32_e32 v54, v56, v52
	s_waitcnt vmcnt(32)
	v_pk_add_f32 v[52:53], v[50:51], v[190:191]
	v_pk_add_f32 v[50:51], v[48:49], v[188:189]
	v_add_u32_e32 v209, 0x160000, v208
	global_load_dwordx4 v[176:179], v209, s[16:17]
	global_load_dwordx4 v[180:183], v209, s[16:17] offset:64
	global_load_dwordx4 v[184:187], v209, s[16:17] offset:512
	global_load_dwordx4 v[188:191], v209, s[16:17] offset:576
	v_mul_f32_e32 v49, v53, v53
	v_mul_f32_e32 v48, v51, v51
	v_fmac_f32_e32 v48, v50, v50
	v_fmac_f32_e32 v49, v52, v52
	v_add_f32_e32 v48, v48, v49
	v_add_f32_e32 v48, v54, v48
	ds_bpermute_b32 v49, v147, v48
	global_store_dwordx4 v[72:73], v[50:53], off offset:576
	s_waitcnt lgkmcnt(0)
	v_add_f32_e32 v48, v48, v49
	ds_bpermute_b32 v49, v148, v48
	v_cvt_pk_bf16_f32 v50, v50, v51
	v_cvt_pk_bf16_f32 v51, v52, v53
	global_store_dwordx2 v[70:71], v[50:51], off offset:288
	s_and_saveexec_b64 s[62:63], s[6:7]
	s_cbranch_execz .LBB0_2726
	v_lshlrev_b64 v[50:51], 7, v[64:65]
	v_lshl_add_u64 v[50:51], s[52:53], 0, v[50:51]
	v_lshl_add_u64 v[50:51], s[56:57], 2, v[50:51]
	s_lshl_b32 s18, s3, 2
	v_lshl_add_u64 v[50:51], v[50:51], 0, s[18:19]
	s_waitcnt lgkmcnt(0)
	v_add_f32_e32 v48, v48, v49
	global_store_dword v[50:51], v48, off
.LBB0_2726:
	s_or_b64 exec, exec, s[62:63]
	v_add_u32_e32 v48, 0x90, v142
	s_waitcnt lgkmcnt(0)
	v_ashrrev_i32_e32 v49, 31, v48
	v_lshlrev_b64 v[50:51], 11, v[48:49]
	v_lshl_add_u64 v[54:55], v[50:51], 0, v[140:141]
	v_lshl_add_u64 v[56:57], v[54:55], 2, s[16:17]
	s_nop 0
	v_lshl_add_u64 v[54:55], v[54:55], 1, s[54:55]
	s_waitcnt vmcnt(29)
	v_pk_add_f32 v[46:47], v[46:47], v[194:195]
	v_pk_add_f32 v[44:45], v[44:45], v[192:193]
	v_cvt_pk_bf16_f32 v51, v46, v47
	v_cvt_pk_bf16_f32 v50, v44, v45
	global_store_dwordx4 v[56:57], v[44:47], off
	global_store_dwordx2 v[54:55], v[50:51], off
	s_nop 0
	v_mul_f32_e32 v45, v45, v45
	v_mul_f32_e32 v47, v47, v47
	v_fmac_f32_e32 v45, v44, v44
	v_fmac_f32_e32 v47, v46, v46
	v_add_f32_e32 v44, v45, v47
	s_waitcnt vmcnt(30)
	v_pk_add_f32 v[42:43], v[42:43], v[198:199]
	v_pk_add_f32 v[40:41], v[40:41], v[196:197]
	v_cvt_pk_bf16_f32 v51, v42, v43
	v_cvt_pk_bf16_f32 v50, v40, v41
	global_store_dwordx4 v[56:57], v[40:43], off offset:64
	global_store_dwordx2 v[54:55], v[50:51], off offset:32
	s_nop 0
	v_mul_f32_e32 v41, v41, v41
	v_mul_f32_e32 v43, v43, v43
	v_fmac_f32_e32 v41, v40, v40
	v_fmac_f32_e32 v43, v42, v42
	v_add_f32_e32 v40, v41, v43
	v_add_f32_e32 v40, v44, v40
	s_waitcnt vmcnt(31)
	v_pk_add_f32 v[38:39], v[38:39], v[202:203]
	v_pk_add_f32 v[36:37], v[36:37], v[200:201]
	v_cvt_pk_bf16_f32 v51, v38, v39
	v_cvt_pk_bf16_f32 v50, v36, v37
	global_store_dwordx4 v[56:57], v[36:39], off offset:512
	global_store_dwordx2 v[54:55], v[50:51], off offset:256
	s_nop 0
	v_mul_f32_e32 v37, v37, v37
	v_mul_f32_e32 v39, v39, v39
	v_fmac_f32_e32 v37, v36, v36
	v_fmac_f32_e32 v39, v38, v38
	v_add_f32_e32 v36, v37, v39
	v_add_f32_e32 v38, v40, v36
	s_waitcnt vmcnt(32)
	v_pk_add_f32 v[36:37], v[34:35], v[206:207]
	v_pk_add_f32 v[34:35], v[32:33], v[204:205]
	v_mul_f32_e32 v33, v37, v37
	v_mul_f32_e32 v32, v35, v35
	v_fmac_f32_e32 v32, v34, v34
	v_fmac_f32_e32 v33, v36, v36
	v_add_f32_e32 v32, v32, v33
	v_add_f32_e32 v32, v38, v32
	ds_bpermute_b32 v33, v147, v32
	global_store_dwordx4 v[56:57], v[34:37], off offset:576
	s_waitcnt lgkmcnt(0)
	v_add_f32_e32 v32, v32, v33
	ds_bpermute_b32 v33, v148, v32
	v_cvt_pk_bf16_f32 v34, v34, v35
	v_cvt_pk_bf16_f32 v35, v36, v37
	global_store_dwordx2 v[54:55], v[34:35], off offset:288
	s_and_saveexec_b64 s[62:63], s[6:7]
	s_cbranch_execz .LBB0_2728
	v_lshlrev_b64 v[34:35], 7, v[48:49]
	v_lshl_add_u64 v[34:35], s[52:53], 0, v[34:35]
	v_lshl_add_u64 v[34:35], s[56:57], 2, v[34:35]
	s_lshl_b32 s18, s3, 2
	v_lshl_add_u64 v[34:35], v[34:35], 0, s[18:19]
	s_waitcnt lgkmcnt(0)
	v_add_f32_e32 v32, v32, v33
	global_store_dword v[34:35], v32, off
.LBB0_2728:
	s_or_b64 exec, exec, s[62:63]
	v_add_u32_e32 v32, 0xa0, v142
	s_waitcnt lgkmcnt(0)
	v_ashrrev_i32_e32 v33, 31, v32
	v_lshlrev_b64 v[34:35], 11, v[32:33]
	v_lshl_add_u64 v[38:39], v[34:35], 0, v[140:141]
	v_lshl_add_u64 v[40:41], v[38:39], 2, s[16:17]
	s_nop 0
	v_lshl_add_u64 v[38:39], v[38:39], 1, s[54:55]
	s_waitcnt vmcnt(25)
	v_pk_add_f32 v[30:31], v[30:31], v[162:163]
	v_pk_add_f32 v[28:29], v[28:29], v[160:161]
	v_cvt_pk_bf16_f32 v35, v30, v31
	v_cvt_pk_bf16_f32 v34, v28, v29
	global_store_dwordx4 v[40:41], v[28:31], off
	global_store_dwordx2 v[38:39], v[34:35], off
	s_nop 0
	v_mul_f32_e32 v29, v29, v29
	v_mul_f32_e32 v31, v31, v31
	v_fmac_f32_e32 v29, v28, v28
	v_fmac_f32_e32 v31, v30, v30
	v_add_f32_e32 v28, v29, v31
	s_waitcnt vmcnt(26)
	v_pk_add_f32 v[26:27], v[26:27], v[166:167]
	v_pk_add_f32 v[24:25], v[24:25], v[164:165]
	v_cvt_pk_bf16_f32 v35, v26, v27
	v_cvt_pk_bf16_f32 v34, v24, v25
	global_store_dwordx4 v[40:41], v[24:27], off offset:64
	global_store_dwordx2 v[38:39], v[34:35], off offset:32
	s_nop 0
	v_mul_f32_e32 v25, v25, v25
	v_mul_f32_e32 v27, v27, v27
	v_fmac_f32_e32 v25, v24, v24
	v_fmac_f32_e32 v27, v26, v26
	v_add_f32_e32 v24, v25, v27
	v_add_f32_e32 v24, v28, v24
	s_waitcnt vmcnt(27)
	v_pk_add_f32 v[22:23], v[22:23], v[170:171]
	v_pk_add_f32 v[20:21], v[20:21], v[168:169]
	v_cvt_pk_bf16_f32 v35, v22, v23
	v_cvt_pk_bf16_f32 v34, v20, v21
	global_store_dwordx4 v[40:41], v[20:23], off offset:512
	global_store_dwordx2 v[38:39], v[34:35], off offset:256
	s_nop 0
	v_mul_f32_e32 v21, v21, v21
	v_mul_f32_e32 v23, v23, v23
	v_fmac_f32_e32 v21, v20, v20
	v_fmac_f32_e32 v23, v22, v22
	v_add_f32_e32 v20, v21, v23
	v_add_f32_e32 v22, v24, v20
	s_waitcnt vmcnt(28)
	v_pk_add_f32 v[20:21], v[18:19], v[174:175]
	v_pk_add_f32 v[18:19], v[16:17], v[172:173]
	v_mul_f32_e32 v17, v21, v21
	v_mul_f32_e32 v16, v19, v19
	v_fmac_f32_e32 v16, v18, v18
	v_fmac_f32_e32 v17, v20, v20
	v_add_f32_e32 v16, v16, v17
	v_add_f32_e32 v16, v22, v16
	ds_bpermute_b32 v17, v147, v16
	global_store_dwordx4 v[40:41], v[18:21], off offset:576
	s_waitcnt lgkmcnt(0)
	v_add_f32_e32 v16, v16, v17
	ds_bpermute_b32 v17, v148, v16
	v_cvt_pk_bf16_f32 v18, v18, v19
	v_cvt_pk_bf16_f32 v19, v20, v21
	global_store_dwordx2 v[38:39], v[18:19], off offset:288
	s_and_saveexec_b64 s[62:63], s[6:7]
	s_cbranch_execz .LBB0_2730
	v_lshlrev_b64 v[18:19], 7, v[32:33]
	v_lshl_add_u64 v[18:19], s[52:53], 0, v[18:19]
	v_lshl_add_u64 v[18:19], s[56:57], 2, v[18:19]
	s_lshl_b32 s18, s3, 2
	v_lshl_add_u64 v[18:19], v[18:19], 0, s[18:19]
	s_waitcnt lgkmcnt(0)
	v_add_f32_e32 v16, v16, v17
	global_store_dword v[18:19], v16, off
.LBB0_2730:
	s_or_b64 exec, exec, s[62:63]
	v_add_u32_e32 v16, 0xb0, v142
	s_waitcnt lgkmcnt(0)
	v_ashrrev_i32_e32 v17, 31, v16
	v_lshlrev_b64 v[18:19], 11, v[16:17]
	v_lshl_add_u64 v[22:23], v[18:19], 0, v[140:141]
	v_lshl_add_u64 v[24:25], v[22:23], 2, s[16:17]
	s_nop 0
	v_lshl_add_u64 v[22:23], v[22:23], 1, s[54:55]
	s_waitcnt vmcnt(21)
	v_pk_add_f32 v[14:15], v[14:15], v[178:179]
	v_pk_add_f32 v[12:13], v[12:13], v[176:177]
	v_cvt_pk_bf16_f32 v19, v14, v15
	v_cvt_pk_bf16_f32 v18, v12, v13
	global_store_dwordx4 v[24:25], v[12:15], off
	global_store_dwordx2 v[22:23], v[18:19], off
	s_nop 0
	v_mul_f32_e32 v13, v13, v13
	v_mul_f32_e32 v15, v15, v15
	v_fmac_f32_e32 v13, v12, v12
	v_fmac_f32_e32 v15, v14, v14
	v_add_f32_e32 v12, v13, v15
	s_waitcnt vmcnt(22)
	v_pk_add_f32 v[10:11], v[10:11], v[182:183]
	v_pk_add_f32 v[8:9], v[8:9], v[180:181]
	v_cvt_pk_bf16_f32 v19, v10, v11
	v_cvt_pk_bf16_f32 v18, v8, v9
	global_store_dwordx4 v[24:25], v[8:11], off offset:64
	global_store_dwordx2 v[22:23], v[18:19], off offset:32
	s_nop 0
	v_mul_f32_e32 v9, v9, v9
	v_mul_f32_e32 v11, v11, v11
	v_fmac_f32_e32 v9, v8, v8
	v_fmac_f32_e32 v11, v10, v10
	v_add_f32_e32 v8, v9, v11
	v_add_f32_e32 v8, v12, v8
	s_waitcnt vmcnt(23)
	v_pk_add_f32 v[6:7], v[6:7], v[186:187]
	v_pk_add_f32 v[4:5], v[4:5], v[184:185]
	v_cvt_pk_bf16_f32 v19, v6, v7
	v_cvt_pk_bf16_f32 v18, v4, v5
	global_store_dwordx4 v[24:25], v[4:7], off offset:512
	global_store_dwordx2 v[22:23], v[18:19], off offset:256
	s_nop 0
	v_mul_f32_e32 v5, v5, v5
	v_mul_f32_e32 v7, v7, v7
	v_fmac_f32_e32 v5, v4, v4
	v_fmac_f32_e32 v7, v6, v6
	v_add_f32_e32 v4, v5, v7
	v_add_f32_e32 v6, v8, v4
	s_waitcnt vmcnt(24)
	v_pk_add_f32 v[4:5], v[2:3], v[190:191]
	v_pk_add_f32 v[2:3], v[0:1], v[188:189]
	v_mul_f32_e32 v1, v5, v5
	v_mul_f32_e32 v0, v3, v3
	v_fmac_f32_e32 v0, v2, v2
	v_fmac_f32_e32 v1, v4, v4
	v_add_f32_e32 v0, v0, v1
	v_add_f32_e32 v0, v6, v0
	ds_bpermute_b32 v1, v147, v0
	global_store_dwordx4 v[24:25], v[2:5], off offset:576
	s_waitcnt lgkmcnt(0)
	v_add_f32_e32 v0, v0, v1
	ds_bpermute_b32 v1, v148, v0
	v_cvt_pk_bf16_f32 v2, v2, v3
	v_cvt_pk_bf16_f32 v3, v4, v5
	global_store_dwordx2 v[22:23], v[2:3], off offset:288
	s_and_saveexec_b64 s[62:63], s[6:7]
	s_cbranch_execz .LBB0_2732
	v_lshlrev_b64 v[2:3], 7, v[16:17]
	v_lshl_add_u64 v[2:3], s[52:53], 0, v[2:3]
	v_lshl_add_u64 v[2:3], s[56:57], 2, v[2:3]
	s_lshl_b32 s18, s3, 2
	v_lshl_add_u64 v[2:3], v[2:3], 0, s[18:19]
	s_waitcnt lgkmcnt(0)
	v_add_f32_e32 v0, v0, v1
	global_store_dword v[2:3], v0, off

.LBB0_2920:
	v_lshl_add_u32 v142, s38, 8, v144
	v_lshl_add_u32 v140, s14, 8, v146
	v_lshl_add_u32 v208, v142, 11, v140
	v_lshlrev_b32_e32 v208, 2, v208
	global_load_dwordx4 v[160:163], v208, s[12:13]
	global_load_dwordx4 v[164:167], v208, s[12:13] offset:64
	global_load_dwordx4 v[168:171], v208, s[12:13] offset:512
	global_load_dwordx4 v[172:175], v208, s[12:13] offset:576
	v_add_u32_e32 v209, 0x20000, v208
	global_load_dwordx4 v[176:179], v209, s[12:13]
	global_load_dwordx4 v[180:183], v209, s[12:13] offset:64
	global_load_dwordx4 v[184:187], v209, s[12:13] offset:512
	global_load_dwordx4 v[188:191], v209, s[12:13] offset:576
	v_add_u32_e32 v209, 0x40000, v208
	global_load_dwordx4 v[192:195], v209, s[12:13]
	global_load_dwordx4 v[196:199], v209, s[12:13] offset:64
	global_load_dwordx4 v[200:203], v209, s[12:13] offset:512
	global_load_dwordx4 v[204:207], v209, s[12:13] offset:576
	v_ashrrev_i32_e32 v143, 31, v142
	v_ashrrev_i32_e32 v141, 31, v140
	v_lshlrev_b64 v[152:153], 11, v[142:143]
	v_lshl_add_u64 v[156:157], v[152:153], 0, v[140:141]
	v_lshl_add_u64 v[158:159], v[156:157], 2, s[12:13]
	s_nop 0
	v_lshl_add_u64 v[156:157], v[156:157], 1, s[54:55]
	s_lshl_b32 s38, s14, 2
	s_ashr_i32 s39, s38, 31
	s_waitcnt vmcnt(11)
	v_pk_add_f32 v[154:155], v[126:127], v[162:163]
	v_pk_add_f32 v[152:153], v[124:125], v[160:161]
	v_cvt_pk_bf16_f32 v125, v154, v155
	v_cvt_pk_bf16_f32 v124, v152, v153
	global_store_dwordx2 v[156:157], v[124:125], off
	s_nop 0
	v_mul_f32_e32 v153, v153, v153
	v_mul_f32_e32 v155, v155, v155
	v_fmac_f32_e32 v153, v152, v152
	v_fmac_f32_e32 v155, v154, v154
	v_add_f32_e32 v152, v153, v155
	s_waitcnt vmcnt(11)
	v_pk_add_f32 v[126:127], v[122:123], v[166:167]
	v_pk_add_f32 v[124:125], v[120:121], v[164:165]
	v_cvt_pk_bf16_f32 v121, v126, v127
	v_cvt_pk_bf16_f32 v120, v124, v125
	global_store_dwordx2 v[156:157], v[120:121], off offset:32
	s_nop 0
	v_mul_f32_e32 v125, v125, v125
	v_mul_f32_e32 v127, v127, v127
	v_fmac_f32_e32 v125, v124, v124
	v_fmac_f32_e32 v127, v126, v126
	v_add_f32_e32 v124, v125, v127
	v_add_f32_e32 v124, v152, v124
	s_waitcnt vmcnt(11)
	v_pk_add_f32 v[122:123], v[118:119], v[170:171]
	v_pk_add_f32 v[120:121], v[116:117], v[168:169]
	v_cvt_pk_bf16_f32 v117, v122, v123
	v_cvt_pk_bf16_f32 v116, v120, v121
	global_store_dwordx2 v[156:157], v[116:117], off offset:256
	s_nop 0
	v_mul_f32_e32 v121, v121, v121
	v_mul_f32_e32 v123, v123, v123
	v_fmac_f32_e32 v121, v120, v120
	v_fmac_f32_e32 v123, v122, v122
	v_add_f32_e32 v120, v121, v123
	v_add_f32_e32 v120, v124, v120
	s_waitcnt vmcnt(11)
	v_pk_add_f32 v[114:115], v[114:115], v[174:175]
	v_pk_add_f32 v[116:117], v[112:113], v[172:173]
	v_add_u32_e32 v209, 0x60000, v208
	global_load_dwordx4 v[160:163], v209, s[12:13]
	global_load_dwordx4 v[164:167], v209, s[12:13] offset:64
	global_load_dwordx4 v[168:171], v209, s[12:13] offset:512
	global_load_dwordx4 v[172:175], v209, s[12:13] offset:576
	v_mul_f32_e32 v113, v115, v115
	v_mul_f32_e32 v112, v117, v117
	v_fmac_f32_e32 v112, v116, v116
	v_fmac_f32_e32 v113, v114, v114
	v_add_f32_e32 v112, v112, v113
	v_add_f32_e32 v112, v120, v112
	ds_bpermute_b32 v113, v147, v112
	v_cvt_pk_bf16_f32 v116, v116, v117
	v_cvt_pk_bf16_f32 v117, v114, v115
	global_store_dwordx2 v[156:157], v[116:117], off offset:288
	s_waitcnt lgkmcnt(0)
	v_add_f32_e32 v112, v112, v113
	ds_bpermute_b32 v113, v148, v112
	s_and_saveexec_b64 s[40:41], s[6:7]
	s_cbranch_execz .LBB0_2922
	v_lshlrev_b64 v[114:115], 7, v[142:143]
	v_lshl_add_u64 v[114:115], s[52:53], 0, v[114:115]
	v_lshl_add_u64 v[114:115], s[38:39], 2, v[114:115]
	s_lshl_b32 s14, s3, 2
	v_lshl_add_u64 v[114:115], v[114:115], 0, s[14:15]
	s_waitcnt lgkmcnt(0)
	v_add_f32_e32 v112, v112, v113
	global_store_dword v[114:115], v112, off
.LBB0_2922:
	s_or_b64 exec, exec, s[40:41]
	v_or_b32_e32 v112, 16, v142
	s_waitcnt lgkmcnt(0)
	v_ashrrev_i32_e32 v113, 31, v112
	v_lshlrev_b64 v[114:115], 11, v[112:113]
	v_lshl_add_u64 v[118:119], v[114:115], 0, v[140:141]
	v_lshl_add_u64 v[120:121], v[118:119], 2, s[12:13]
	s_nop 0
	v_lshl_add_u64 v[118:119], v[118:119], 1, s[54:55]
	s_waitcnt vmcnt(15)
	v_pk_add_f32 v[116:117], v[110:111], v[178:179]
	v_pk_add_f32 v[114:115], v[108:109], v[176:177]
	v_cvt_pk_bf16_f32 v109, v116, v117
	v_cvt_pk_bf16_f32 v108, v114, v115
	global_store_dwordx2 v[118:119], v[108:109], off
	s_nop 0
	v_mul_f32_e32 v115, v115, v115
	v_mul_f32_e32 v117, v117, v117
	v_fmac_f32_e32 v115, v114, v114
	v_fmac_f32_e32 v117, v116, v116
	v_add_f32_e32 v114, v115, v117
	s_waitcnt vmcnt(15)
	v_pk_add_f32 v[110:111], v[106:107], v[182:183]
	v_pk_add_f32 v[108:109], v[104:105], v[180:181]
	v_cvt_pk_bf16_f32 v105, v110, v111
	v_cvt_pk_bf16_f32 v104, v108, v109
	global_store_dwordx2 v[118:119], v[104:105], off offset:32
	s_nop 0
	v_mul_f32_e32 v109, v109, v109
	v_mul_f32_e32 v111, v111, v111
	v_fmac_f32_e32 v109, v108, v108
	v_fmac_f32_e32 v111, v110, v110
	v_add_f32_e32 v108, v109, v111
	v_add_f32_e32 v108, v114, v108
	s_waitcnt vmcnt(15)
	v_pk_add_f32 v[106:107], v[102:103], v[186:187]
	v_pk_add_f32 v[104:105], v[100:101], v[184:185]
	v_cvt_pk_bf16_f32 v101, v106, v107
	v_cvt_pk_bf16_f32 v100, v104, v105
	global_store_dwordx2 v[118:119], v[100:101], off offset:256
	s_nop 0
	v_mul_f32_e32 v105, v105, v105
	v_mul_f32_e32 v107, v107, v107
	v_fmac_f32_e32 v105, v104, v104
	v_fmac_f32_e32 v107, v106, v106
	v_add_f32_e32 v104, v105, v107
	v_add_f32_e32 v104, v108, v104
	s_waitcnt vmcnt(15)
	v_pk_add_f32 v[98:99], v[98:99], v[190:191]
	v_pk_add_f32 v[100:101], v[96:97], v[188:189]
	v_add_u32_e32 v209, 0x100000, v208
	global_load_dwordx4 v[176:179], v209, s[12:13]
	global_load_dwordx4 v[180:183], v209, s[12:13] offset:64
	global_load_dwordx4 v[184:187], v209, s[12:13] offset:512
	global_load_dwordx4 v[188:191], v209, s[12:13] offset:576
	v_mul_f32_e32 v97, v99, v99
	v_mul_f32_e32 v96, v101, v101
	v_fmac_f32_e32 v96, v100, v100
	v_fmac_f32_e32 v97, v98, v98
	v_add_f32_e32 v96, v96, v97
	v_add_f32_e32 v96, v104, v96
	ds_bpermute_b32 v97, v147, v96
	v_cvt_pk_bf16_f32 v100, v100, v101
	v_cvt_pk_bf16_f32 v101, v98, v99
	global_store_dwordx2 v[118:119], v[100:101], off offset:288
	s_waitcnt lgkmcnt(0)
	v_add_f32_e32 v96, v96, v97
	ds_bpermute_b32 v97, v148, v96
	s_and_saveexec_b64 s[40:41], s[6:7]
	s_cbranch_execz .LBB0_2924
	v_lshlrev_b64 v[98:99], 7, v[112:113]
	v_lshl_add_u64 v[98:99], s[52:53], 0, v[98:99]
	v_lshl_add_u64 v[98:99], s[38:39], 2, v[98:99]
	s_lshl_b32 s14, s3, 2
	v_lshl_add_u64 v[98:99], v[98:99], 0, s[14:15]
	s_waitcnt lgkmcnt(0)
	v_add_f32_e32 v96, v96, v97
	global_store_dword v[98:99], v96, off
.LBB0_2924:
	s_or_b64 exec, exec, s[40:41]
	v_or_b32_e32 v96, 32, v142
	s_waitcnt lgkmcnt(0)
	v_ashrrev_i32_e32 v97, 31, v96
	v_lshlrev_b64 v[98:99], 11, v[96:97]
	v_lshl_add_u64 v[102:103], v[98:99], 0, v[140:141]
	v_lshl_add_u64 v[104:105], v[102:103], 2, s[12:13]
	s_nop 0
	v_lshl_add_u64 v[102:103], v[102:103], 1, s[54:55]
	s_waitcnt vmcnt(19)
	v_pk_add_f32 v[100:101], v[94:95], v[194:195]
	v_pk_add_f32 v[98:99], v[92:93], v[192:193]
	v_cvt_pk_bf16_f32 v93, v100, v101
	v_cvt_pk_bf16_f32 v92, v98, v99
	global_store_dwordx2 v[102:103], v[92:93], off
	s_nop 0
	v_mul_f32_e32 v99, v99, v99
	v_mul_f32_e32 v101, v101, v101
	v_fmac_f32_e32 v99, v98, v98
	v_fmac_f32_e32 v101, v100, v100
	v_add_f32_e32 v98, v99, v101
	s_waitcnt vmcnt(19)
	v_pk_add_f32 v[94:95], v[90:91], v[198:199]
	v_pk_add_f32 v[92:93], v[88:89], v[196:197]
	v_cvt_pk_bf16_f32 v89, v94, v95
	v_cvt_pk_bf16_f32 v88, v92, v93
	global_store_dwordx2 v[102:103], v[88:89], off offset:32
	s_nop 0
	v_mul_f32_e32 v93, v93, v93
	v_mul_f32_e32 v95, v95, v95
	v_fmac_f32_e32 v93, v92, v92
	v_fmac_f32_e32 v95, v94, v94
	v_add_f32_e32 v92, v93, v95
	v_add_f32_e32 v92, v98, v92
	s_waitcnt vmcnt(19)
	v_pk_add_f32 v[90:91], v[86:87], v[202:203]
	v_pk_add_f32 v[88:89], v[84:85], v[200:201]
	v_cvt_pk_bf16_f32 v85, v90, v91
	v_cvt_pk_bf16_f32 v84, v88, v89
	global_store_dwordx2 v[102:103], v[84:85], off offset:256
	s_nop 0
	v_mul_f32_e32 v89, v89, v89
	v_mul_f32_e32 v91, v91, v91
	v_fmac_f32_e32 v89, v88, v88
	v_fmac_f32_e32 v91, v90, v90
	v_add_f32_e32 v88, v89, v91
	v_add_f32_e32 v88, v92, v88
	s_waitcnt vmcnt(19)
	v_pk_add_f32 v[82:83], v[82:83], v[206:207]
	v_pk_add_f32 v[84:85], v[80:81], v[204:205]
	v_add_u32_e32 v209, 0x120000, v208
	global_load_dwordx4 v[192:195], v209, s[12:13]
	global_load_dwordx4 v[196:199], v209, s[12:13] offset:64
	global_load_dwordx4 v[200:203], v209, s[12:13] offset:512
	global_load_dwordx4 v[204:207], v209, s[12:13] offset:576
	v_mul_f32_e32 v81, v83, v83
	v_mul_f32_e32 v80, v85, v85
	v_fmac_f32_e32 v80, v84, v84
	v_fmac_f32_e32 v81, v82, v82
	v_add_f32_e32 v80, v80, v81
	v_add_f32_e32 v80, v88, v80
	ds_bpermute_b32 v81, v147, v80
	v_cvt_pk_bf16_f32 v84, v84, v85
	v_cvt_pk_bf16_f32 v85, v82, v83
	global_store_dwordx2 v[102:103], v[84:85], off offset:288
	s_waitcnt lgkmcnt(0)
	v_add_f32_e32 v80, v80, v81
	ds_bpermute_b32 v81, v148, v80
	s_and_saveexec_b64 s[40:41], s[6:7]
	s_cbranch_execz .LBB0_2926
	v_lshlrev_b64 v[82:83], 7, v[96:97]
	v_lshl_add_u64 v[82:83], s[52:53], 0, v[82:83]
	v_lshl_add_u64 v[82:83], s[38:39], 2, v[82:83]
	s_lshl_b32 s14, s3, 2
	v_lshl_add_u64 v[82:83], v[82:83], 0, s[14:15]
	s_waitcnt lgkmcnt(0)
	v_add_f32_e32 v80, v80, v81
	global_store_dword v[82:83], v80, off
.LBB0_2926:
	s_or_b64 exec, exec, s[40:41]
	v_or_b32_e32 v80, 48, v142
	s_waitcnt lgkmcnt(0)
	v_ashrrev_i32_e32 v81, 31, v80
	v_lshlrev_b64 v[82:83], 11, v[80:81]
	v_lshl_add_u64 v[86:87], v[82:83], 0, v[140:141]
	v_lshl_add_u64 v[88:89], v[86:87], 2, s[12:13]
	s_nop 0
	v_lshl_add_u64 v[86:87], v[86:87], 1, s[54:55]
	s_waitcnt vmcnt(20)
	v_pk_add_f32 v[84:85], v[78:79], v[162:163]
	v_pk_add_f32 v[82:83], v[76:77], v[160:161]
	v_cvt_pk_bf16_f32 v77, v84, v85
	v_cvt_pk_bf16_f32 v76, v82, v83
	global_store_dwordx2 v[86:87], v[76:77], off
	s_nop 0
	v_mul_f32_e32 v83, v83, v83
	v_mul_f32_e32 v85, v85, v85
	v_fmac_f32_e32 v83, v82, v82
	v_fmac_f32_e32 v85, v84, v84
	v_add_f32_e32 v82, v83, v85
	s_waitcnt vmcnt(20)
	v_pk_add_f32 v[78:79], v[74:75], v[166:167]
	v_pk_add_f32 v[76:77], v[72:73], v[164:165]
	v_cvt_pk_bf16_f32 v73, v78, v79
	v_cvt_pk_bf16_f32 v72, v76, v77
	global_store_dwordx2 v[86:87], v[72:73], off offset:32
	s_nop 0
	v_mul_f32_e32 v77, v77, v77
	v_mul_f32_e32 v79, v79, v79
	v_fmac_f32_e32 v77, v76, v76
	v_fmac_f32_e32 v79, v78, v78
	v_add_f32_e32 v76, v77, v79
	v_add_f32_e32 v76, v82, v76
	s_waitcnt vmcnt(20)
	v_pk_add_f32 v[74:75], v[70:71], v[170:171]
	v_pk_add_f32 v[72:73], v[68:69], v[168:169]
	v_cvt_pk_bf16_f32 v69, v74, v75
	v_cvt_pk_bf16_f32 v68, v72, v73
	global_store_dwordx2 v[86:87], v[68:69], off offset:256
	s_nop 0
	v_mul_f32_e32 v73, v73, v73
	v_mul_f32_e32 v75, v75, v75
	v_fmac_f32_e32 v73, v72, v72
	v_fmac_f32_e32 v75, v74, v74
	v_add_f32_e32 v72, v73, v75
	v_add_f32_e32 v72, v76, v72
	s_waitcnt vmcnt(20)
	v_pk_add_f32 v[66:67], v[66:67], v[174:175]
	v_pk_add_f32 v[68:69], v[64:65], v[172:173]
	v_add_u32_e32 v209, 0x140000, v208
	global_load_dwordx4 v[160:163], v209, s[12:13]
	global_load_dwordx4 v[164:167], v209, s[12:13] offset:64
	global_load_dwordx4 v[168:171], v209, s[12:13] offset:512
	global_load_dwordx4 v[172:175], v209, s[12:13] offset:576
	v_mul_f32_e32 v65, v67, v67
	v_mul_f32_e32 v64, v69, v69
	v_fmac_f32_e32 v64, v68, v68
	v_fmac_f32_e32 v65, v66, v66
	v_add_f32_e32 v64, v64, v65
	v_add_f32_e32 v64, v72, v64
	ds_bpermute_b32 v65, v147, v64
	v_cvt_pk_bf16_f32 v68, v68, v69
	v_cvt_pk_bf16_f32 v69, v66, v67
	global_store_dwordx2 v[86:87], v[68:69], off offset:288
	s_waitcnt lgkmcnt(0)
	v_add_f32_e32 v64, v64, v65
	ds_bpermute_b32 v65, v148, v64
	s_and_saveexec_b64 s[40:41], s[6:7]
	s_cbranch_execz .LBB0_2928
	v_lshlrev_b64 v[66:67], 7, v[80:81]
	v_lshl_add_u64 v[66:67], s[52:53], 0, v[66:67]
	v_lshl_add_u64 v[66:67], s[38:39], 2, v[66:67]
	s_lshl_b32 s14, s3, 2
	v_lshl_add_u64 v[66:67], v[66:67], 0, s[14:15]
	s_waitcnt lgkmcnt(0)
	v_add_f32_e32 v64, v64, v65
	global_store_dword v[66:67], v64, off
.LBB0_2928:
	s_or_b64 exec, exec, s[40:41]
	v_add_u32_e32 v64, 0x80, v142
	s_waitcnt lgkmcnt(0)
	v_ashrrev_i32_e32 v65, 31, v64
	v_lshlrev_b64 v[66:67], 11, v[64:65]
	v_lshl_add_u64 v[70:71], v[66:67], 0, v[140:141]
	v_lshl_add_u64 v[72:73], v[70:71], 2, s[12:13]
	s_nop 0
	v_lshl_add_u64 v[70:71], v[70:71], 1, s[54:55]
	s_waitcnt vmcnt(20)
	v_pk_add_f32 v[68:69], v[62:63], v[178:179]
	v_pk_add_f32 v[66:67], v[60:61], v[176:177]
	v_cvt_pk_bf16_f32 v61, v68, v69
	v_cvt_pk_bf16_f32 v60, v66, v67
	global_store_dwordx2 v[70:71], v[60:61], off
	s_nop 0
	v_mul_f32_e32 v67, v67, v67
	v_mul_f32_e32 v69, v69, v69
	v_fmac_f32_e32 v67, v66, v66
	v_fmac_f32_e32 v69, v68, v68
	v_add_f32_e32 v66, v67, v69
	s_waitcnt vmcnt(20)
	v_pk_add_f32 v[62:63], v[58:59], v[182:183]
	v_pk_add_f32 v[60:61], v[56:57], v[180:181]
	v_cvt_pk_bf16_f32 v57, v62, v63
	v_cvt_pk_bf16_f32 v56, v60, v61
	global_store_dwordx2 v[70:71], v[56:57], off offset:32
	s_nop 0
	v_mul_f32_e32 v61, v61, v61
	v_mul_f32_e32 v63, v63, v63
	v_fmac_f32_e32 v61, v60, v60
	v_fmac_f32_e32 v63, v62, v62
	v_add_f32_e32 v60, v61, v63
	v_add_f32_e32 v60, v66, v60
	s_waitcnt vmcnt(20)
	v_pk_add_f32 v[58:59], v[54:55], v[186:187]
	v_pk_add_f32 v[56:57], v[52:53], v[184:185]
	v_cvt_pk_bf16_f32 v53, v58, v59
	v_cvt_pk_bf16_f32 v52, v56, v57
	global_store_dwordx2 v[70:71], v[52:53], off offset:256
	s_nop 0
	v_mul_f32_e32 v57, v57, v57
	v_mul_f32_e32 v59, v59, v59
	v_fmac_f32_e32 v57, v56, v56
	v_fmac_f32_e32 v59, v58, v58
	v_add_f32_e32 v56, v57, v59
	v_add_f32_e32 v56, v60, v56
	s_waitcnt vmcnt(20)
	v_pk_add_f32 v[50:51], v[50:51], v[190:191]
	v_pk_add_f32 v[52:53], v[48:49], v[188:189]
	v_add_u32_e32 v209, 0x160000, v208
	global_load_dwordx4 v[176:179], v209, s[12:13]
	global_load_dwordx4 v[180:183], v209, s[12:13] offset:64
	global_load_dwordx4 v[184:187], v209, s[12:13] offset:512
	global_load_dwordx4 v[188:191], v209, s[12:13] offset:576
	v_mul_f32_e32 v49, v51, v51
	v_mul_f32_e32 v48, v53, v53
	v_fmac_f32_e32 v48, v52, v52
	v_fmac_f32_e32 v49, v50, v50
	v_add_f32_e32 v48, v48, v49
	v_add_f32_e32 v48, v56, v48
	ds_bpermute_b32 v49, v147, v48
	v_cvt_pk_bf16_f32 v52, v52, v53
	v_cvt_pk_bf16_f32 v53, v50, v51
	global_store_dwordx2 v[70:71], v[52:53], off offset:288
	s_waitcnt lgkmcnt(0)
	v_add_f32_e32 v48, v48, v49
	ds_bpermute_b32 v49, v148, v48
	s_and_saveexec_b64 s[40:41], s[6:7]
	s_cbranch_execz .LBB0_2930
	v_lshlrev_b64 v[50:51], 7, v[64:65]
	v_lshl_add_u64 v[50:51], s[52:53], 0, v[50:51]
	v_lshl_add_u64 v[50:51], s[38:39], 2, v[50:51]
	s_lshl_b32 s14, s3, 2
	v_lshl_add_u64 v[50:51], v[50:51], 0, s[14:15]
	s_waitcnt lgkmcnt(0)
	v_add_f32_e32 v48, v48, v49
	global_store_dword v[50:51], v48, off
.LBB0_2930:
	s_or_b64 exec, exec, s[40:41]
	v_add_u32_e32 v48, 0x90, v142
	s_waitcnt lgkmcnt(0)
	v_ashrrev_i32_e32 v49, 31, v48
	v_lshlrev_b64 v[50:51], 11, v[48:49]
	v_lshl_add_u64 v[54:55], v[50:51], 0, v[140:141]
	v_lshl_add_u64 v[56:57], v[54:55], 2, s[12:13]
	s_nop 0
	v_lshl_add_u64 v[54:55], v[54:55], 1, s[54:55]
	s_waitcnt vmcnt(20)
	v_pk_add_f32 v[52:53], v[46:47], v[194:195]
	v_pk_add_f32 v[50:51], v[44:45], v[192:193]
	v_cvt_pk_bf16_f32 v45, v52, v53
	v_cvt_pk_bf16_f32 v44, v50, v51
	global_store_dwordx2 v[54:55], v[44:45], off
	s_nop 0
	v_mul_f32_e32 v51, v51, v51
	v_mul_f32_e32 v53, v53, v53
	v_fmac_f32_e32 v51, v50, v50
	v_fmac_f32_e32 v53, v52, v52
	v_add_f32_e32 v50, v51, v53
	s_waitcnt vmcnt(20)
	v_pk_add_f32 v[46:47], v[42:43], v[198:199]
	v_pk_add_f32 v[44:45], v[40:41], v[196:197]
	v_cvt_pk_bf16_f32 v41, v46, v47
	v_cvt_pk_bf16_f32 v40, v44, v45
	global_store_dwordx2 v[54:55], v[40:41], off offset:32
	s_nop 0
	v_mul_f32_e32 v45, v45, v45
	v_mul_f32_e32 v47, v47, v47
	v_fmac_f32_e32 v45, v44, v44
	v_fmac_f32_e32 v47, v46, v46
	v_add_f32_e32 v44, v45, v47
	v_add_f32_e32 v44, v50, v44
	s_waitcnt vmcnt(20)
	v_pk_add_f32 v[42:43], v[38:39], v[202:203]
	v_pk_add_f32 v[40:41], v[36:37], v[200:201]
	v_cvt_pk_bf16_f32 v37, v42, v43
	v_cvt_pk_bf16_f32 v36, v40, v41
	global_store_dwordx2 v[54:55], v[36:37], off offset:256
	s_nop 0
	v_mul_f32_e32 v41, v41, v41
	v_mul_f32_e32 v43, v43, v43
	v_fmac_f32_e32 v41, v40, v40
	v_fmac_f32_e32 v43, v42, v42
	v_add_f32_e32 v40, v41, v43
	v_add_f32_e32 v40, v44, v40
	s_waitcnt vmcnt(20)
	v_pk_add_f32 v[34:35], v[34:35], v[206:207]
	v_pk_add_f32 v[36:37], v[32:33], v[204:205]
	v_mul_f32_e32 v33, v35, v35
	v_mul_f32_e32 v32, v37, v37
	v_fmac_f32_e32 v32, v36, v36
	v_fmac_f32_e32 v33, v34, v34
	v_add_f32_e32 v32, v32, v33
	v_add_f32_e32 v32, v40, v32
	ds_bpermute_b32 v33, v147, v32
	v_cvt_pk_bf16_f32 v36, v36, v37
	v_cvt_pk_bf16_f32 v37, v34, v35
	global_store_dwordx2 v[54:55], v[36:37], off offset:288
	s_waitcnt lgkmcnt(0)
	v_add_f32_e32 v32, v32, v33
	ds_bpermute_b32 v33, v148, v32
	s_and_saveexec_b64 s[40:41], s[6:7]
	s_cbranch_execz .LBB0_2932
	v_lshlrev_b64 v[34:35], 7, v[48:49]
	v_lshl_add_u64 v[34:35], s[52:53], 0, v[34:35]
	v_lshl_add_u64 v[34:35], s[38:39], 2, v[34:35]
	s_lshl_b32 s14, s3, 2
	v_lshl_add_u64 v[34:35], v[34:35], 0, s[14:15]
	s_waitcnt lgkmcnt(0)
	v_add_f32_e32 v32, v32, v33
	global_store_dword v[34:35], v32, off
.LBB0_2932:
	s_or_b64 exec, exec, s[40:41]
	v_add_u32_e32 v32, 0xa0, v142
	s_waitcnt lgkmcnt(0)
	v_ashrrev_i32_e32 v33, 31, v32
	v_lshlrev_b64 v[34:35], 11, v[32:33]
	v_lshl_add_u64 v[38:39], v[34:35], 0, v[140:141]
	v_lshl_add_u64 v[40:41], v[38:39], 2, s[12:13]
	s_nop 0
	v_lshl_add_u64 v[38:39], v[38:39], 1, s[54:55]
	s_waitcnt vmcnt(16)
	v_pk_add_f32 v[36:37], v[30:31], v[162:163]
	v_pk_add_f32 v[34:35], v[28:29], v[160:161]
	v_cvt_pk_bf16_f32 v29, v36, v37
	v_cvt_pk_bf16_f32 v28, v34, v35
	global_store_dwordx2 v[38:39], v[28:29], off
	s_nop 0
	v_mul_f32_e32 v35, v35, v35
	v_mul_f32_e32 v37, v37, v37
	v_fmac_f32_e32 v35, v34, v34
	v_fmac_f32_e32 v37, v36, v36
	v_add_f32_e32 v34, v35, v37
	s_waitcnt vmcnt(16)
	v_pk_add_f32 v[30:31], v[26:27], v[166:167]
	v_pk_add_f32 v[28:29], v[24:25], v[164:165]
	v_cvt_pk_bf16_f32 v25, v30, v31
	v_cvt_pk_bf16_f32 v24, v28, v29
	global_store_dwordx2 v[38:39], v[24:25], off offset:32
	s_nop 0
	v_mul_f32_e32 v29, v29, v29
	v_mul_f32_e32 v31, v31, v31
	v_fmac_f32_e32 v29, v28, v28
	v_fmac_f32_e32 v31, v30, v30
	v_add_f32_e32 v28, v29, v31
	v_add_f32_e32 v28, v34, v28
	s_waitcnt vmcnt(16)
	v_pk_add_f32 v[26:27], v[22:23], v[170:171]
	v_pk_add_f32 v[24:25], v[20:21], v[168:169]
	v_cvt_pk_bf16_f32 v21, v26, v27
	v_cvt_pk_bf16_f32 v20, v24, v25
	global_store_dwordx2 v[38:39], v[20:21], off offset:256
	s_nop 0
	v_mul_f32_e32 v25, v25, v25
	v_mul_f32_e32 v27, v27, v27
	v_fmac_f32_e32 v25, v24, v24
	v_fmac_f32_e32 v27, v26, v26
	v_add_f32_e32 v24, v25, v27
	v_add_f32_e32 v24, v28, v24
	s_waitcnt vmcnt(16)
	v_pk_add_f32 v[18:19], v[18:19], v[174:175]
	v_pk_add_f32 v[20:21], v[16:17], v[172:173]
	v_mul_f32_e32 v17, v19, v19
	v_mul_f32_e32 v16, v21, v21
	v_fmac_f32_e32 v16, v20, v20
	v_fmac_f32_e32 v17, v18, v18
	v_add_f32_e32 v16, v16, v17
	v_add_f32_e32 v16, v24, v16
	ds_bpermute_b32 v17, v147, v16
	v_cvt_pk_bf16_f32 v20, v20, v21
	v_cvt_pk_bf16_f32 v21, v18, v19
	global_store_dwordx2 v[38:39], v[20:21], off offset:288
	s_waitcnt lgkmcnt(0)
	v_add_f32_e32 v16, v16, v17
	ds_bpermute_b32 v17, v148, v16
	s_and_saveexec_b64 s[40:41], s[6:7]
	s_cbranch_execz .LBB0_2934
	v_lshlrev_b64 v[18:19], 7, v[32:33]
	v_lshl_add_u64 v[18:19], s[52:53], 0, v[18:19]
	v_lshl_add_u64 v[18:19], s[38:39], 2, v[18:19]
	s_lshl_b32 s14, s3, 2
	v_lshl_add_u64 v[18:19], v[18:19], 0, s[14:15]
	s_waitcnt lgkmcnt(0)
	v_add_f32_e32 v16, v16, v17
	global_store_dword v[18:19], v16, off
.LBB0_2934:
	s_or_b64 exec, exec, s[40:41]
	v_add_u32_e32 v16, 0xb0, v142
	s_waitcnt lgkmcnt(0)
	v_ashrrev_i32_e32 v17, 31, v16
	v_lshlrev_b64 v[18:19], 11, v[16:17]
	v_lshl_add_u64 v[22:23], v[18:19], 0, v[140:141]
	v_lshl_add_u64 v[24:25], v[22:23], 2, s[12:13]
	s_nop 0
	v_lshl_add_u64 v[22:23], v[22:23], 1, s[54:55]
	s_waitcnt vmcnt(12)
	v_pk_add_f32 v[20:21], v[14:15], v[178:179]
	v_pk_add_f32 v[18:19], v[12:13], v[176:177]
	v_cvt_pk_bf16_f32 v13, v20, v21
	v_cvt_pk_bf16_f32 v12, v18, v19
	global_store_dwordx2 v[22:23], v[12:13], off
	s_nop 0
	v_mul_f32_e32 v19, v19, v19
	v_mul_f32_e32 v21, v21, v21
	v_fmac_f32_e32 v19, v18, v18
	v_fmac_f32_e32 v21, v20, v20
	v_add_f32_e32 v18, v19, v21
	s_waitcnt vmcnt(12)
	v_pk_add_f32 v[14:15], v[10:11], v[182:183]
	v_pk_add_f32 v[12:13], v[8:9], v[180:181]
	v_cvt_pk_bf16_f32 v9, v14, v15
	v_cvt_pk_bf16_f32 v8, v12, v13
	global_store_dwordx2 v[22:23], v[8:9], off offset:32
	s_nop 0
	v_mul_f32_e32 v13, v13, v13
	v_mul_f32_e32 v15, v15, v15
	v_fmac_f32_e32 v13, v12, v12
	v_fmac_f32_e32 v15, v14, v14
	v_add_f32_e32 v12, v13, v15
	v_add_f32_e32 v12, v18, v12
	s_waitcnt vmcnt(12)
	v_pk_add_f32 v[10:11], v[6:7], v[186:187]
	v_pk_add_f32 v[8:9], v[4:5], v[184:185]
	v_cvt_pk_bf16_f32 v5, v10, v11
	v_cvt_pk_bf16_f32 v4, v8, v9
	global_store_dwordx2 v[22:23], v[4:5], off offset:256
	s_nop 0
	v_mul_f32_e32 v9, v9, v9
	v_mul_f32_e32 v11, v11, v11
	v_fmac_f32_e32 v9, v8, v8
	v_fmac_f32_e32 v11, v10, v10
	v_add_f32_e32 v8, v9, v11
	v_add_f32_e32 v8, v12, v8
	s_waitcnt vmcnt(12)
	v_pk_add_f32 v[2:3], v[2:3], v[190:191]
	v_pk_add_f32 v[4:5], v[0:1], v[188:189]
	v_mul_f32_e32 v1, v3, v3
	v_mul_f32_e32 v0, v5, v5
	v_fmac_f32_e32 v0, v4, v4
	v_fmac_f32_e32 v1, v2, v2
	v_add_f32_e32 v0, v0, v1
	v_add_f32_e32 v0, v8, v0
	ds_bpermute_b32 v1, v147, v0
	v_cvt_pk_bf16_f32 v4, v4, v5
	v_cvt_pk_bf16_f32 v5, v2, v3
	global_store_dwordx2 v[22:23], v[4:5], off offset:288
	s_waitcnt lgkmcnt(0)
	v_add_f32_e32 v0, v0, v1
	ds_bpermute_b32 v1, v148, v0
	s_and_saveexec_b64 s[40:41], s[6:7]
	s_cbranch_execz .LBB0_2936
	v_lshlrev_b64 v[2:3], 7, v[16:17]
	v_lshl_add_u64 v[2:3], s[52:53], 0, v[2:3]
	v_lshl_add_u64 v[2:3], s[38:39], 2, v[2:3]
	s_lshl_b32 s14, s3, 2
	v_lshl_add_u64 v[2:3], v[2:3], 0, s[14:15]
	s_waitcnt lgkmcnt(0)
	v_add_f32_e32 v0, v0, v1
	global_store_dword v[2:3], v0, off
